# attention loops (both layers): waves 4-7 staggered half an iteration behind waves 0-3 (3 LDS stages, mid-iteration barrier) + ssd1 remap
# speedup vs baseline: 1.0252x; 1.0087x over previous
.LBB0_657:
	s_or_b64 exec, exec, s[38:39]
	s_mov_b64 s[0:1], s[92:93]
	s_waitcnt lgkmcnt(0)
	s_barrier
	s_load_dwordx2 s[4:5], s[0:1], 0xd0
	v_readlane_b32 s0, v255, 0
	s_cmpk_lt_i32 s0, 0x100
	s_cselect_b64 s[6:7], -1, 0
	v_writelane_b32 v255, s6, 21
	s_cmpk_gt_i32 s0, 0xff
	s_nop 0
	v_writelane_b32 v255, s7, 22
	s_cbranch_scc1 .LBB0_671
	s_waitcnt lgkmcnt(0)
	s_add_u32 s0, s4, 0xa866000
	s_addc_u32 s1, s5, 0
	s_add_u32 s11, s4, 0xb526000
	s_addc_u32 s18, s5, 0
	s_add_u32 s19, s4, 0xc1e6000
	s_addc_u32 s20, s5, 0
	s_add_u32 s6, s4, 0x32dc000
	v_and_b32_e32 v0, 64, v165
	s_addc_u32 s7, s5, 0
	s_movk_i32 s21, 0xffe0
	s_movk_i32 s24, 0x300
	v_mov_b64_e32 v[140:141], s[0:1]
	s_mov_b32 s9, 0
	v_mov_b32_e32 v143, 0
	s_mov_b32 s10, 0x3e16c740
	s_mov_b32 s25, 0x2aaaaaab
	s_movk_i32 s26, 0x2200
	s_movk_i32 s27, 0x84
	s_mov_b64 s[12:13], 0x6000
	s_mov_b64 s[14:15], 0x100
	s_add_i32 s28, 0, 0x6800
	v_readfirstlane_b32 s100, v164
	s_nop 3
	s_lshr_b32 s100, s100, 8
	v_xor_b32_e32 v160, 32, v165
	v_add_u32_e32 v161, 64, v0
	v_readlane_b32 s29, v255, 8
	v_readlane_b32 s30, v255, 0
	s_branch .LBB0_662
.LBB0_659:
	s_waitcnt vmcnt(4)
	v_add3_u32 v124, 0, v169, v170
	ds_read_b128 v[32:35], v124
	s_waitcnt vmcnt(3)
	ds_read_b128 v[120:123], v124 offset:32
	s_waitcnt lgkmcnt(1)
	v_mfma_f32_32x32x16_bf16 v[80:95], v[32:35], v[108:111], 0
	ds_read_b128 v[32:35], v124 offset:6656
	s_waitcnt lgkmcnt(1)
	v_mfma_f32_32x32x16_bf16 v[80:95], v[120:123], v[104:107], v[80:95]
	s_waitcnt lgkmcnt(0)
	v_mfma_f32_32x32x16_bf16 v[64:79], v[32:35], v[108:111], 0
	ds_read_b128 v[32:35], v124 offset:13312
	s_waitcnt lgkmcnt(0)
	v_mfma_f32_32x32x16_bf16 v[48:63], v[32:35], v[108:111], 0
	ds_read_b128 v[32:35], v124 offset:19968
	s_waitcnt lgkmcnt(0)
	v_mfma_f32_32x32x16_bf16 v[32:47], v[32:35], v[108:111], 0
	ds_read_b128 v[108:111], v124 offset:6688
	s_waitcnt lgkmcnt(0)
	v_mfma_f32_32x32x16_bf16 v[64:79], v[108:111], v[104:107], v[64:79]
	ds_read_b128 v[108:111], v124 offset:13344
	s_waitcnt lgkmcnt(0)
	v_mfma_f32_32x32x16_bf16 v[48:63], v[108:111], v[104:107], v[48:63]
	ds_read_b128 v[108:111], v124 offset:20000
	s_waitcnt lgkmcnt(0)
	v_mfma_f32_32x32x16_bf16 v[32:47], v[108:111], v[104:107], v[32:47]
	ds_read_b128 v[104:107], v124 offset:64
	s_waitcnt lgkmcnt(0)
	v_mfma_f32_32x32x16_bf16 v[80:95], v[104:107], v[100:103], v[80:95]
	ds_read_b128 v[104:107], v124 offset:6720
	s_waitcnt lgkmcnt(0)
	v_mfma_f32_32x32x16_bf16 v[64:79], v[104:107], v[100:103], v[64:79]
	ds_read_b128 v[104:107], v124 offset:13376
	s_waitcnt lgkmcnt(0)
	v_mfma_f32_32x32x16_bf16 v[48:63], v[104:107], v[100:103], v[48:63]
	ds_read_b128 v[104:107], v124 offset:20032
	s_waitcnt lgkmcnt(0)
	v_mfma_f32_32x32x16_bf16 v[32:47], v[104:107], v[100:103], v[32:47]
	ds_read_b128 v[100:103], v124 offset:96
	s_waitcnt lgkmcnt(0)
	v_mfma_f32_32x32x16_bf16 v[80:95], v[100:103], v[96:99], v[80:95]
	ds_read_b128 v[100:103], v124 offset:6752
	s_waitcnt lgkmcnt(0)
	v_mfma_f32_32x32x16_bf16 v[64:79], v[100:103], v[96:99], v[64:79]
	ds_read_b128 v[100:103], v124 offset:13408
	s_waitcnt lgkmcnt(0)
	v_mfma_f32_32x32x16_bf16 v[48:63], v[100:103], v[96:99], v[48:63]
	ds_read_b128 v[100:103], v124 offset:20064
	s_waitcnt lgkmcnt(0)
	v_mfma_f32_32x32x16_bf16 v[32:47], v[100:103], v[96:99], v[32:47]
	ds_read_b128 v[96:99], v124 offset:128
	s_waitcnt lgkmcnt(0)
	v_mfma_f32_32x32x16_bf16 v[80:95], v[96:99], v[112:115], v[80:95]
	ds_read_b128 v[96:99], v124 offset:6784
	s_waitcnt lgkmcnt(0)
	v_mfma_f32_32x32x16_bf16 v[64:79], v[96:99], v[112:115], v[64:79]
	ds_read_b128 v[96:99], v124 offset:13440
	s_waitcnt lgkmcnt(0)
	v_mfma_f32_32x32x16_bf16 v[48:63], v[96:99], v[112:115], v[48:63]
	ds_read_b128 v[96:99], v124 offset:160
	ds_read_b128 v[100:103], v124 offset:13472
	ds_read_b128 v[104:107], v124 offset:6816
	s_waitcnt lgkmcnt(2)
	v_mfma_f32_32x32x16_bf16 v[80:95], v[96:99], v[116:119], v[80:95]
	ds_read_b128 v[96:99], v124 offset:20128
	ds_read_b128 v[108:111], v124 offset:20096
	s_waitcnt lgkmcnt(2)
	v_mfma_f32_32x32x16_bf16 v[64:79], v[104:107], v[116:119], v[64:79]
	s_nop 7
	v_max_f32_e32 v120, v81, v81
	v_max_f32_e32 v121, v80, v80
	v_max_f32_e32 v120, v121, v120
	v_max3_f32 v120, v120, v82, v83
	v_max3_f32 v120, v120, v84, v85
	v_max3_f32 v104, v120, v86, v87
	v_max3_f32 v104, v104, v88, v89
	v_max3_f32 v104, v104, v90, v91
	v_max3_f32 v104, v104, v92, v93
	v_max3_f32 v104, v104, v94, v95
	v_max3_f32 v104, v104, v64, v65
	v_mfma_f32_32x32x16_bf16 v[48:63], v[100:103], v[116:119], v[48:63]
	v_max3_f32 v104, v104, v66, v67
	v_max3_f32 v100, v104, v68, v69
	v_max3_f32 v100, v100, v70, v71
	v_max3_f32 v100, v100, v72, v73
	v_max3_f32 v100, v100, v74, v75
	v_max3_f32 v100, v100, v76, v77
	v_max3_f32 v100, v100, v78, v79
	s_waitcnt lgkmcnt(0)
	v_mfma_f32_32x32x16_bf16 v[32:47], v[108:111], v[112:115], v[32:47]
	s_nop 2
	v_max3_f32 v100, v100, v48, v49
	v_max3_f32 v100, v100, v50, v51
	v_max3_f32 v100, v100, v52, v53
	v_max3_f32 v100, v100, v54, v55
	v_max3_f32 v100, v100, v56, v57
	v_max3_f32 v100, v100, v58, v59
	v_max3_f32 v100, v100, v60, v61
	v_mfma_f32_32x32x16_bf16 v[32:47], v[96:99], v[116:119], v[32:47]
	v_max3_f32 v100, v100, v62, v63
	s_nop 10
	v_max3_f32 v96, v100, v32, v33
	v_max3_f32 v96, v96, v34, v35
	v_max3_f32 v96, v96, v36, v37
	v_max3_f32 v96, v96, v38, v39
	v_max3_f32 v96, v96, v40, v41
	v_max3_f32 v96, v96, v42, v43
	v_max3_f32 v96, v96, v44, v45
	v_max3_f32 v96, v96, v46, v47
	ds_bpermute_b32 v97, v147, v96
	s_waitcnt lgkmcnt(0)
	v_max3_f32 v96, v171, v96, v97
	v_cmp_gt_f32_e32 vcc, v96, v171
	s_cbranch_vccz .LBB0_670
	v_sub_f32_e32 v97, v171, v96
	v_exp_f32_e32 v98, v97
	s_nop 0
	v_pk_mul_f32 v[30:31], v[30:31], v[98:99] op_sel_hi:[1,0]
	v_pk_mul_f32 v[28:29], v[28:29], v[98:99] op_sel_hi:[1,0]
	v_pk_mul_f32 v[26:27], v[26:27], v[98:99] op_sel_hi:[1,0]
	v_pk_mul_f32 v[24:25], v[24:25], v[98:99] op_sel_hi:[1,0]
	v_pk_mul_f32 v[22:23], v[22:23], v[98:99] op_sel_hi:[1,0]
	v_pk_mul_f32 v[20:21], v[20:21], v[98:99] op_sel_hi:[1,0]
	v_pk_mul_f32 v[18:19], v[18:19], v[98:99] op_sel_hi:[1,0]
	v_pk_mul_f32 v[16:17], v[16:17], v[98:99] op_sel_hi:[1,0]
	v_pk_mul_f32 v[14:15], v[14:15], v[98:99] op_sel_hi:[1,0]
	v_pk_mul_f32 v[12:13], v[12:13], v[98:99] op_sel_hi:[1,0]
	v_pk_mul_f32 v[10:11], v[10:11], v[98:99] op_sel_hi:[1,0]
	v_pk_mul_f32 v[8:9], v[8:9], v[98:99] op_sel_hi:[1,0]
	v_pk_mul_f32 v[6:7], v[6:7], v[98:99] op_sel_hi:[1,0]
	v_pk_mul_f32 v[4:5], v[4:5], v[98:99] op_sel_hi:[1,0]
	v_pk_mul_f32 v[2:3], v[2:3], v[98:99] op_sel_hi:[1,0]
	v_pk_mul_f32 v[0:1], v[0:1], v[98:99] op_sel_hi:[1,0]
	v_mul_f32_e32 v149, v149, v98
.LBB0_661:
	s_waitcnt lgkmcnt(0)
	s_barrier
	v_sub_f32_e32 v80, v80, v96
	v_exp_f32_e32 v80, v80
	v_sub_f32_e32 v81, v81, v96
	v_sub_f32_e32 v82, v82, v96
	v_exp_f32_e32 v81, v81
	v_exp_f32_e32 v82, v82
	v_sub_f32_e32 v83, v83, v96
	v_exp_f32_e32 v83, v83
	v_sub_f32_e32 v84, v84, v96
	v_add_f32_e32 v97, 0, v80
	v_exp_f32_e32 v84, v84
	v_sub_f32_e32 v85, v85, v96
	v_add_f32_e32 v97, v81, v97
	v_exp_f32_e32 v85, v85
	v_sub_f32_e32 v86, v86, v96
	v_add_f32_e32 v97, v82, v97
	v_exp_f32_e32 v86, v86
	v_sub_f32_e32 v87, v87, v96
	v_add_f32_e32 v97, v83, v97
	v_exp_f32_e32 v87, v87
	v_sub_f32_e32 v88, v88, v96
	v_add_f32_e32 v97, v84, v97
	v_exp_f32_e32 v88, v88
	v_sub_f32_e32 v89, v89, v96
	v_add_f32_e32 v97, v85, v97
	v_exp_f32_e32 v89, v89
	v_sub_f32_e32 v90, v90, v96
	v_add_f32_e32 v97, v86, v97
	v_exp_f32_e32 v90, v90
	v_sub_f32_e32 v91, v91, v96
	v_add_f32_e32 v97, v87, v97
	v_exp_f32_e32 v91, v91
	v_sub_f32_e32 v92, v92, v96
	v_add_f32_e32 v97, v88, v97
	v_exp_f32_e32 v92, v92
	v_sub_f32_e32 v93, v93, v96
	v_add_f32_e32 v97, v89, v97
	v_exp_f32_e32 v93, v93
	v_sub_f32_e32 v94, v94, v96
	v_add_f32_e32 v97, v90, v97
	v_exp_f32_e32 v94, v94
	v_sub_f32_e32 v95, v95, v96
	v_add_f32_e32 v97, v91, v97
	v_exp_f32_e32 v95, v95
	v_sub_f32_e32 v64, v64, v96
	v_add_f32_e32 v97, v92, v97
	v_exp_f32_e32 v98, v64
	v_sub_f32_e32 v65, v65, v96
	v_add_f32_e32 v64, v93, v97
	v_exp_f32_e32 v97, v65
	v_sub_f32_e32 v65, v66, v96
	v_add_f32_e32 v64, v94, v64
	v_exp_f32_e32 v99, v65
	v_sub_f32_e32 v65, v67, v96
	v_add_f32_e32 v64, v95, v64
	v_exp_f32_e32 v100, v65
	v_sub_f32_e32 v65, v68, v96
	v_add_f32_e32 v64, v98, v64
	v_exp_f32_e32 v68, v65
	v_sub_f32_e32 v65, v69, v96
	v_add_f32_e32 v64, v97, v64
	v_exp_f32_e32 v69, v65
	v_sub_f32_e32 v65, v70, v96
	v_add_f32_e32 v64, v99, v64
	v_exp_f32_e32 v70, v65
	v_sub_f32_e32 v65, v71, v96
	v_add_f32_e32 v64, v100, v64
	v_exp_f32_e32 v71, v65
	v_sub_f32_e32 v65, v72, v96
	v_add_f32_e32 v64, v68, v64
	v_exp_f32_e32 v72, v65
	v_sub_f32_e32 v65, v73, v96
	v_add_f32_e32 v64, v69, v64
	v_exp_f32_e32 v73, v65
	v_sub_f32_e32 v65, v74, v96
	v_add_f32_e32 v64, v70, v64
	v_exp_f32_e32 v74, v65
	v_sub_f32_e32 v65, v75, v96
	v_add_f32_e32 v64, v71, v64
	v_exp_f32_e32 v75, v65
	v_sub_f32_e32 v65, v76, v96
	v_add_f32_e32 v64, v72, v64
	v_exp_f32_e32 v76, v65
	v_sub_f32_e32 v65, v77, v96
	v_add_f32_e32 v64, v73, v64
	v_exp_f32_e32 v77, v65
	v_sub_f32_e32 v65, v78, v96
	v_add_f32_e32 v64, v74, v64
	v_exp_f32_e32 v78, v65
	v_sub_f32_e32 v65, v79, v96
	v_add_f32_e32 v64, v75, v64
	v_exp_f32_e32 v79, v65
	v_sub_f32_e32 v48, v48, v96
	v_add_f32_e32 v64, v76, v64
	v_exp_f32_e32 v101, v48
	v_sub_f32_e32 v49, v49, v96
	v_add_f32_e32 v48, v77, v64
	v_exp_f32_e32 v102, v49
	v_sub_f32_e32 v49, v50, v96
	v_add_f32_e32 v48, v78, v48
	v_exp_f32_e32 v103, v49
	v_sub_f32_e32 v49, v51, v96
	v_add_f32_e32 v48, v79, v48
	v_exp_f32_e32 v104, v49
	v_sub_f32_e32 v49, v52, v96
	v_add_f32_e32 v48, v101, v48
	v_exp_f32_e32 v105, v49
	v_add_f32_e32 v48, v102, v48
	v_add_f32_e32 v48, v103, v48
	v_add_f32_e32 v48, v104, v48
	v_add_f32_e32 v106, v105, v48
	v_sub_f32_e32 v48, v53, v96
	v_exp_f32_e32 v107, v48
	v_sub_f32_e32 v48, v54, v96
	v_exp_f32_e32 v108, v48
	v_sub_f32_e32 v48, v55, v96
	v_add3_u32 v110, s28, v142, v162
	v_exp_f32_e32 v109, v48
	ds_read2_b64 v[48:51], v110 offset1:2
	v_sub_f32_e32 v52, v56, v96
	v_exp_f32_e32 v111, v52
	v_cvt_pk_bf16_f32 v52, v80, v81
	v_cvt_pk_bf16_f32 v53, v82, v83
	v_cvt_pk_bf16_f32 v54, v84, v85
	v_cvt_pk_bf16_f32 v55, v86, v87
	v_add_u32_e32 v80, 0x2000, v110
	ds_read2_b64 v[64:67], v80 offset0:32 offset1:34
	s_waitcnt lgkmcnt(1)
	v_mfma_f32_32x32x16_bf16 v[16:31], v[48:51], v[52:55], v[16:31]
	v_add_f32_e32 v48, v107, v106
	v_add_f32_e32 v48, v108, v48
	v_add_f32_e32 v48, v109, v48
	v_add_f32_e32 v56, v111, v48
	v_sub_f32_e32 v48, v57, v96
	v_exp_f32_e32 v81, v48
	ds_read2_b64 v[48:51], v110 offset0:4 offset1:6
	s_waitcnt lgkmcnt(1)
	v_mfma_f32_32x32x16_bf16 v[0:15], v[64:67], v[52:55], v[0:15]
	v_sub_f32_e32 v52, v58, v96
	v_exp_f32_e32 v82, v52
	v_cvt_pk_bf16_f32 v52, v88, v89
	v_cvt_pk_bf16_f32 v53, v90, v91
	v_cvt_pk_bf16_f32 v54, v92, v93
	v_cvt_pk_bf16_f32 v55, v94, v95
	ds_read2_b64 v[64:67], v80 offset0:36 offset1:38
	v_sub_f32_e32 v32, v32, v96
	s_waitcnt lgkmcnt(1)
	v_mfma_f32_32x32x16_bf16 v[16:31], v[48:51], v[52:55], v[16:31]
	v_add_f32_e32 v48, v81, v56
	v_add_f32_e32 v83, v82, v48
	v_sub_f32_e32 v48, v59, v96
	v_exp_f32_e32 v84, v48
	v_sub_f32_e32 v48, v60, v96
	v_exp_f32_e32 v60, v48
	ds_read2_b64 v[48:51], v110 offset0:8 offset1:10
	s_waitcnt lgkmcnt(1)
	v_mfma_f32_32x32x16_bf16 v[0:15], v[64:67], v[52:55], v[0:15]
	v_sub_f32_e32 v52, v61, v96
	v_exp_f32_e32 v61, v52
	v_cvt_pk_bf16_f32 v52, v98, v97
	v_cvt_pk_bf16_f32 v53, v99, v100
	v_cvt_pk_bf16_f32 v54, v68, v69
	v_cvt_pk_bf16_f32 v55, v70, v71
	ds_read2_b64 v[56:59], v80 offset0:40 offset1:42
	v_exp_f32_e32 v65, v32
	s_waitcnt lgkmcnt(1)
	v_mfma_f32_32x32x16_bf16 v[16:31], v[48:51], v[52:55], v[16:31]
	v_sub_f32_e32 v48, v62, v96
	v_exp_f32_e32 v62, v48
	v_add_f32_e32 v48, v84, v83
	v_add_f32_e32 v48, v60, v48
	v_add_f32_e32 v48, v61, v48
	v_add_f32_e32 v64, v62, v48
	ds_read2_b64 v[48:51], v110 offset0:12 offset1:14
	s_waitcnt lgkmcnt(1)
	v_mfma_f32_32x32x16_bf16 v[0:15], v[56:59], v[52:55], v[0:15]
	ds_read2_b64 v[56:59], v80 offset0:44 offset1:46
	v_sub_f32_e32 v52, v63, v96
	v_exp_f32_e32 v63, v52
	v_cvt_pk_bf16_f32 v52, v72, v73
	v_cvt_pk_bf16_f32 v53, v74, v75
	v_cvt_pk_bf16_f32 v54, v76, v77
	v_cvt_pk_bf16_f32 v55, v78, v79
	v_sub_f32_e32 v32, v33, v96
	v_exp_f32_e32 v66, v32
	s_waitcnt lgkmcnt(1)
	v_mfma_f32_32x32x16_bf16 v[16:31], v[48:51], v[52:55], v[16:31]
	ds_read2_b64 v[48:51], v110 offset0:16 offset1:18
	v_sub_f32_e32 v32, v34, v96
	v_cvt_pk_bf16_f32 v33, v103, v104
	v_cvt_pk_bf16_f32 v34, v105, v107
	v_sub_f32_e32 v36, v36, v96
	v_sub_f32_e32 v40, v40, v96
	v_sub_f32_e32 v46, v46, v96
	s_waitcnt lgkmcnt(1)
	v_mfma_f32_32x32x16_bf16 v[0:15], v[56:59], v[52:55], v[0:15]
	ds_read2_b64 v[52:55], v80 offset0:48 offset1:50
	v_exp_f32_e32 v56, v32
	v_sub_f32_e32 v57, v35, v96
	v_cvt_pk_bf16_f32 v32, v101, v102
	v_cvt_pk_bf16_f32 v35, v108, v109
	v_exp_f32_e32 v58, v36
	v_sub_f32_e32 v36, v37, v96
	s_waitcnt lgkmcnt(1)
	v_mfma_f32_32x32x16_bf16 v[16:31], v[48:51], v[32:35], v[16:31]
	ds_read2_b64 v[48:51], v110 offset0:20 offset1:22
	v_exp_f32_e32 v59, v36
	v_sub_f32_e32 v36, v38, v96
	v_exp_f32_e32 v57, v57
	v_exp_f32_e32 v46, v46
	v_add_f32_e32 v64, v63, v64
	s_lshl_b32 s8, s31, 7
	s_waitcnt lgkmcnt(1)
	v_mfma_f32_32x32x16_bf16 v[0:15], v[52:55], v[32:35], v[0:15]
	v_exp_f32_e32 v52, v36
	v_sub_f32_e32 v53, v39, v96
	ds_read2_b64 v[36:39], v80 offset0:52 offset1:54
	v_cvt_pk_bf16_f32 v32, v111, v81
	v_cvt_pk_bf16_f32 v33, v82, v84
	v_cvt_pk_bf16_f32 v34, v60, v61
	v_cvt_pk_bf16_f32 v35, v62, v63
	v_exp_f32_e32 v53, v53
	v_exp_f32_e32 v54, v40
	s_waitcnt lgkmcnt(1)
	v_mfma_f32_32x32x16_bf16 v[16:31], v[48:51], v[32:35], v[16:31]
	ds_read2_b64 v[48:51], v110 offset0:24 offset1:26
	v_sub_f32_e32 v40, v41, v96
	v_exp_f32_e32 v55, v40
	v_sub_f32_e32 v40, v42, v96
	v_exp_f32_e32 v60, v40
	v_sub_f32_e32 v40, v43, v96
	s_add_i32 s30, s30, s90
	s_waitcnt lgkmcnt(1)
	v_mfma_f32_32x32x16_bf16 v[0:15], v[36:39], v[32:35], v[0:15]
	ds_read2_b64 v[36:39], v80 offset0:56 offset1:58
	v_cvt_pk_bf16_f32 v32, v65, v66
	v_cvt_pk_bf16_f32 v33, v56, v57
	v_cvt_pk_bf16_f32 v34, v58, v59
	v_cvt_pk_bf16_f32 v35, v52, v53
	s_add_i32 s29, s29, s33
	s_cmpk_gt_i32 s30, 0xff
	s_waitcnt lgkmcnt(1)
	v_mfma_f32_32x32x16_bf16 v[16:31], v[48:51], v[32:35], v[16:31]
	v_exp_f32_e32 v48, v40
	v_sub_f32_e32 v40, v44, v96
	v_exp_f32_e32 v44, v40
	v_sub_f32_e32 v40, v45, v96
	v_exp_f32_e32 v45, v40
	ds_read2_b64 v[40:43], v110 offset0:28 offset1:30
	s_waitcnt lgkmcnt(1)
	v_mfma_f32_32x32x16_bf16 v[0:15], v[36:39], v[32:35], v[0:15]
	v_sub_f32_e32 v32, v47, v96
	v_exp_f32_e32 v47, v32
	v_cvt_pk_bf16_f32 v32, v54, v55
	v_cvt_pk_bf16_f32 v33, v60, v48
	v_cvt_pk_bf16_f32 v34, v44, v45
	v_cvt_pk_bf16_f32 v35, v46, v47
	ds_read2_b64 v[36:39], v80 offset0:60 offset1:62
	s_waitcnt lgkmcnt(0)
	v_mfma_f32_32x32x16_bf16 v[16:31], v[40:43], v[32:35], v[16:31]
	v_add_f32_e32 v40, v65, v64
	v_add_f32_e32 v40, v66, v40
	v_add_f32_e32 v40, v56, v40
	v_add_f32_e32 v40, v57, v40
	v_add_f32_e32 v40, v58, v40
	v_add_f32_e32 v40, v59, v40
	v_add_f32_e32 v40, v52, v40
	v_add_f32_e32 v40, v53, v40
	v_add_f32_e32 v40, v54, v40
	v_add_f32_e32 v40, v55, v40
	v_add_f32_e32 v40, v60, v40
	v_add_f32_e32 v40, v48, v40
	v_add_f32_e32 v40, v44, v40
	v_add_f32_e32 v40, v45, v40
	v_add_f32_e32 v40, v46, v40
	v_add_f32_e32 v40, v47, v40
	v_add_f32_e32 v40, v149, v40
	ds_bpermute_b32 v41, v147, v40
	v_mfma_f32_32x32x16_bf16 v[0:15], v[36:39], v[32:35], v[0:15]
	s_barrier
	s_cselect_b32 s101, 1, 0
	s_cmp_lg_u32 s100, 0
	s_cbranch_scc1 .Latt0_nofin
	s_barrier
.Latt0_nofin:
	s_cmp_lg_u32 s101, 0
	s_waitcnt lgkmcnt(0)
	v_add_f32_e32 v32, v40, v41
	v_div_scale_f32 v33, s[0:1], v32, v32, 1.0
	v_rcp_f32_e32 v34, v33
	s_nop 0
	v_fma_f32 v35, -v33, v34, 1.0
	v_fmac_f32_e32 v34, v35, v34
	v_div_scale_f32 v35, vcc, 1.0, v32, 1.0
	v_mul_f32_e32 v36, v35, v34
	v_fma_f32 v37, -v33, v36, v35
	v_fmac_f32_e32 v36, v37, v34
	v_fma_f32 v33, -v33, v36, v35
	v_div_fmas_f32 v33, v33, v34, v36
	v_lshlrev_b64 v[34:35], 11, v[144:145]
	v_div_fixup_f32 v32, v33, v32, 1.0
	v_lshl_add_u64 v[34:35], s[6:7], 0, v[34:35]
	v_lshl_add_u64 v[34:35], v[34:35], 0, s[8:9]
	v_pk_mul_f32 v[16:17], v[16:17], v[32:33] op_sel_hi:[1,0]
	v_pk_mul_f32 v[18:19], v[18:19], v[32:33] op_sel_hi:[1,0]
	v_pk_mul_f32 v[0:1], v[0:1], v[32:33] op_sel_hi:[1,0]
	v_pk_mul_f32 v[2:3], v[2:3], v[32:33] op_sel_hi:[1,0]
	v_lshl_add_u64 v[34:35], v[34:35], 0, v[142:143]
	v_cvt_pk_bf16_f32 v16, v16, v17
	v_cvt_pk_bf16_f32 v17, v18, v19
	v_cvt_pk_bf16_f32 v0, v0, v1
	v_cvt_pk_bf16_f32 v1, v2, v3
	global_store_dwordx2 v[34:35], v[16:17], off
	v_pk_mul_f32 v[16:17], v[20:21], v[32:33] op_sel_hi:[1,0]
	v_pk_mul_f32 v[18:19], v[22:23], v[32:33] op_sel_hi:[1,0]
	global_store_dwordx2 v[34:35], v[0:1], off offset:64
	v_pk_mul_f32 v[0:1], v[4:5], v[32:33] op_sel_hi:[1,0]
	v_pk_mul_f32 v[2:3], v[6:7], v[32:33] op_sel_hi:[1,0]
	v_cvt_pk_bf16_f32 v16, v16, v17
	v_cvt_pk_bf16_f32 v17, v18, v19
	v_cvt_pk_bf16_f32 v0, v0, v1
	v_cvt_pk_bf16_f32 v1, v2, v3
	global_store_dwordx2 v[34:35], v[16:17], off offset:16
	v_pk_mul_f32 v[16:17], v[24:25], v[32:33] op_sel_hi:[1,0]
	v_pk_mul_f32 v[18:19], v[26:27], v[32:33] op_sel_hi:[1,0]
	global_store_dwordx2 v[34:35], v[0:1], off offset:80
	v_pk_mul_f32 v[0:1], v[8:9], v[32:33] op_sel_hi:[1,0]
	v_pk_mul_f32 v[2:3], v[10:11], v[32:33] op_sel_hi:[1,0]
	v_cvt_pk_bf16_f32 v16, v16, v17
	v_cvt_pk_bf16_f32 v17, v18, v19
	v_cvt_pk_bf16_f32 v0, v0, v1
	v_cvt_pk_bf16_f32 v1, v2, v3
	global_store_dwordx2 v[34:35], v[16:17], off offset:32
	v_pk_mul_f32 v[16:17], v[28:29], v[32:33] op_sel_hi:[1,0]
	v_pk_mul_f32 v[18:19], v[30:31], v[32:33] op_sel_hi:[1,0]
	global_store_dwordx2 v[34:35], v[0:1], off offset:96
	v_pk_mul_f32 v[0:1], v[12:13], v[32:33] op_sel_hi:[1,0]
	v_pk_mul_f32 v[2:3], v[14:15], v[32:33] op_sel_hi:[1,0]
	v_cvt_pk_bf16_f32 v16, v16, v17
	v_cvt_pk_bf16_f32 v17, v18, v19
	v_cvt_pk_bf16_f32 v0, v0, v1
	v_cvt_pk_bf16_f32 v1, v2, v3
	global_store_dwordx2 v[34:35], v[16:17], off offset:48
	global_store_dwordx2 v[34:35], v[0:1], off offset:112
	s_cbranch_scc1 .LBB0_671
.LBB0_662:
	s_lshl_b32 s1, s30, 1
	s_and_b32 s2, s1, 14
	s_ashr_i32 s1, s30, 7
	s_add_i32 s35, s2, s1
	s_lshl_b32 s2, s35, 10
	s_lshl_b32 s8, s30, 5
	s_and_b32 s0, s29, 14
	s_and_b32 s31, s35, 3
	s_and_b32 s2, s2, 0xfffff000
	s_and_b32 s34, s8, 0xf00
	s_mul_i32 s16, s35, 0xcc000
	v_mov_b32_e32 v8, v164
	s_mul_hi_i32 s8, s35, 0xcc000
	s_add_u32 s16, s11, s16
	s_waitcnt vmcnt(0)
	v_ashrrev_i32_e32 v17, 1, v8
	s_addc_u32 s17, s18, s8
	v_bfi_b32 v0, s21, v17, v8
	s_or_b32 s2, s2, s34
	v_add_u32_e32 v144, s2, v0
	v_bfe_u32 v9, v8, 5, 1
	v_mad_i64_i32 v[0:1], s[36:37], v144, s24, v[140:141]
	s_mul_i32 s8, s31, 0xc0
	v_lshl_add_u64 v[30:31], v[0:1], 0, s[8:9]
	v_lshlrev_b32_e32 v142, 4, v9
	v_lshl_add_u64 v[10:11], v[30:31], 0, v[142:143]
	global_load_dwordx4 v[0:3], v[10:11], off
	global_load_dwordx4 v[4:7], v[10:11], off offset:32
	global_load_dwordx4 v[12:15], v[10:11], off offset:64
	global_load_dwordx4 v[18:21], v[10:11], off offset:96
	global_load_dwordx4 v[22:25], v[30:31], off offset:144
	global_load_dwordx4 v[26:29], v[30:31], off offset:128
	v_and_b32_e32 v10, 31, v8
	v_and_b32_e32 v11, 0xffffffe0, v17
	v_cmp_eq_u32_e32 vcc, 0, v9
	s_mul_i32 s8, s35, 0x88000
	s_mul_hi_i32 s2, s35, 0x88000
	v_lshlrev_b32_e32 v16, 3, v9
	v_lshlrev_b32_e32 v169, 1, v16
	v_ashrrev_i32_e32 v145, 31, v144
	v_mov_b32_e32 v172, 0xf149f2ca
	s_waitcnt vmcnt(5)
	v_lshlrev_b32_e32 v32, 16, v0
	v_and_b32_e32 v33, 0xffff0000, v0
	v_lshlrev_b32_e32 v0, 16, v1
	v_and_b32_e32 v1, 0xffff0000, v1
	v_pk_mul_f32 v[0:1], v[0:1], s[10:11] op_sel_hi:[1,0]
	v_lshlrev_b32_e32 v34, 16, v2
	v_cvt_pk_bf16_f32 v109, v0, v1
	s_waitcnt vmcnt(2)
	v_lshlrev_b32_e32 v0, 16, v20
	v_and_b32_e32 v1, 0xffff0000, v20
	v_pk_mul_f32 v[0:1], v[0:1], s[10:11] op_sel_hi:[1,0]
	v_and_b32_e32 v35, 0xffff0000, v2
	v_cvt_pk_bf16_f32 v98, v0, v1
	v_lshlrev_b32_e32 v0, 16, v21
	v_and_b32_e32 v1, 0xffff0000, v21
	v_pk_mul_f32 v[0:1], v[0:1], s[10:11] op_sel_hi:[1,0]
	v_lshlrev_b32_e32 v2, 16, v3
	v_cvt_pk_bf16_f32 v99, v0, v1
	v_add_u32_e32 v0, s34, v17
	v_and_b32_e32 v3, 0xffff0000, v3
	v_lshlrev_b32_e32 v36, 16, v4
	v_and_b32_e32 v37, 0xffff0000, v4
	v_lshlrev_b32_e32 v4, 16, v5
	v_and_b32_e32 v5, 0xffff0000, v5
	v_lshlrev_b32_e32 v38, 16, v6
	v_and_b32_e32 v39, 0xffff0000, v6
	v_lshlrev_b32_e32 v6, 16, v7
	v_and_b32_e32 v7, 0xffff0000, v7
	v_ashrrev_i32_e32 v0, 6, v0
	v_pk_mul_f32 v[2:3], v[2:3], s[10:11] op_sel_hi:[1,0]
	v_pk_mul_f32 v[4:5], v[4:5], s[10:11] op_sel_hi:[1,0]
	v_pk_mul_f32 v[6:7], v[6:7], s[10:11] op_sel_hi:[1,0]
	v_cvt_f32_i32_e32 v17, v0
	v_bitop3_b32 v0, v11, 63, v10 bitop3:0xc8
	v_cvt_pk_bf16_f32 v111, v2, v3
	v_cvt_pk_bf16_f32 v105, v4, v5
	v_cvt_pk_bf16_f32 v107, v6, v7
	v_cvt_f32_ubyte0_e32 v11, v0
	global_load_dwordx4 v[0:3], v[30:31], off offset:176
	global_load_dwordx4 v[4:7], v[30:31], off offset:160
	v_lshlrev_b32_e32 v40, 16, v12
	v_and_b32_e32 v41, 0xffff0000, v12
	v_lshlrev_b32_e32 v12, 16, v13
	v_and_b32_e32 v13, 0xffff0000, v13
	v_lshlrev_b32_e32 v42, 16, v14
	v_and_b32_e32 v43, 0xffff0000, v14
	v_lshlrev_b32_e32 v14, 16, v15
	v_and_b32_e32 v15, 0xffff0000, v15
	v_pk_mul_f32 v[12:13], v[12:13], s[10:11] op_sel_hi:[1,0]
	v_pk_mul_f32 v[14:15], v[14:15], s[10:11] op_sel_hi:[1,0]
	v_cvt_pk_bf16_f32 v101, v12, v13
	v_mul_f32_e32 v13, 0.15915494, v17
	v_cvt_pk_bf16_f32 v103, v14, v15
	v_cos_f32_e32 v12, v13
	v_sin_f32_e32 v14, v13
	v_mul_f32_e32 v13, 0x3ea1e89b, v17
	v_mul_f32_e32 v15, 0.15915494, v13
	v_cos_f32_e32 v13, v15
	v_sin_f32_e32 v15, v15
	v_lshlrev_b32_e32 v44, 16, v18
	v_and_b32_e32 v45, 0xffff0000, v18
	v_lshlrev_b32_e32 v18, 16, v19
	v_and_b32_e32 v19, 0xffff0000, v19
	v_pk_mul_f32 v[18:19], v[18:19], s[10:11] op_sel_hi:[1,0]
	s_waitcnt vmcnt(3)
	v_lshlrev_b32_e32 v20, 16, v22
	v_and_b32_e32 v21, 0xffff0000, v22
	v_cvt_pk_bf16_f32 v97, v18, v19
	s_waitcnt vmcnt(2)
	v_lshlrev_b32_e32 v18, 16, v26
	v_and_b32_e32 v19, 0xffff0000, v26
	v_pk_mul_f32 v[30:31], v[14:15], v[20:21]
	v_lshlrev_b32_e32 v22, 16, v23
	v_pk_fma_f32 v[30:31], v[12:13], v[18:19], v[30:31] neg_lo:[0,0,1] neg_hi:[0,0,1]
	v_pk_mul_f32 v[12:13], v[12:13], v[20:21]
	v_and_b32_e32 v23, 0xffff0000, v23
	v_pk_fma_f32 v[12:13], v[14:15], v[18:19], v[12:13]
	v_mul_f32_e32 v14, 0x3dcccccd, v17
	v_mul_f32_e32 v15, 0.15915494, v14
	v_cos_f32_e32 v14, v15
	v_sin_f32_e32 v18, v15
	v_mul_f32_e32 v15, 0x3d0186e3, v17
	v_mul_f32_e32 v19, 0.15915494, v15
	v_cos_f32_e32 v15, v19
	v_sin_f32_e32 v19, v19
	v_lshlrev_b32_e32 v20, 16, v27
	v_and_b32_e32 v21, 0xffff0000, v27
	v_cndmask_b32_e32 v13, v13, v31, vcc
	v_pk_mul_f32 v[26:27], v[18:19], v[22:23]
	v_cndmask_b32_e32 v12, v12, v30, vcc
	v_pk_fma_f32 v[26:27], v[14:15], v[20:21], v[26:27] neg_lo:[0,0,1] neg_hi:[0,0,1]
	v_pk_mul_f32 v[14:15], v[14:15], v[22:23]
	v_lshlrev_b32_e32 v22, 16, v28
	v_pk_fma_f32 v[14:15], v[18:19], v[20:21], v[14:15]
	v_mul_f32_e32 v18, 0x3c23d70b, v17
	v_mul_f32_e32 v19, 0.15915494, v18
	v_cos_f32_e32 v18, v19
	v_sin_f32_e32 v20, v19
	v_mul_f32_e32 v19, 0x3b4f3e39, v17
	v_mul_f32_e32 v21, 0.15915494, v19
	v_cos_f32_e32 v19, v21
	v_sin_f32_e32 v21, v21
	v_cndmask_b32_e32 v15, v15, v27, vcc
	v_cndmask_b32_e32 v14, v14, v26, vcc
	v_lshlrev_b32_e32 v26, 16, v24
	v_and_b32_e32 v27, 0xffff0000, v24
	v_and_b32_e32 v23, 0xffff0000, v28
	v_pk_mul_f32 v[30:31], v[20:21], v[26:27]
	v_pk_mul_f32 v[12:13], v[12:13], s[10:11] op_sel_hi:[1,0]
	v_pk_fma_f32 v[30:31], v[18:19], v[22:23], v[30:31] neg_lo:[0,0,1] neg_hi:[0,0,1]
	v_pk_mul_f32 v[18:19], v[18:19], v[26:27]
	v_pk_mul_f32 v[14:15], v[14:15], s[10:11] op_sel_hi:[1,0]
	v_pk_fma_f32 v[18:19], v[20:21], v[22:23], v[18:19]
	v_mul_f32_e32 v20, 0x3a831270, v17
	v_mul_f32_e32 v17, 0x39a5cb61, v17
	v_mul_f32_e32 v21, 0.15915494, v20
	v_mul_f32_e32 v17, 0.15915494, v17
	v_sin_f32_e32 v22, v21
	v_sin_f32_e32 v23, v17
	v_cos_f32_e32 v20, v21
	v_cos_f32_e32 v21, v17
	v_lshlrev_b32_e32 v24, 16, v25
	v_and_b32_e32 v25, 0xffff0000, v25
	v_cvt_pk_bf16_f32 v112, v12, v13
	v_mul_f32_e32 v13, 0.15915494, v11
	v_lshlrev_b32_e32 v26, 16, v29
	v_and_b32_e32 v27, 0xffff0000, v29
	v_pk_mul_f32 v[28:29], v[22:23], v[24:25]
	v_cvt_pk_bf16_f32 v113, v14, v15
	v_cos_f32_e32 v12, v13
	v_sin_f32_e32 v14, v13
	v_mul_f32_e32 v13, 0x3ea1e89b, v11
	v_pk_fma_f32 v[28:29], v[20:21], v[26:27], v[28:29] neg_lo:[0,0,1] neg_hi:[0,0,1]
	v_pk_mul_f32 v[20:21], v[20:21], v[24:25]
	v_mul_f32_e32 v15, 0.15915494, v13
	v_pk_fma_f32 v[20:21], v[22:23], v[26:27], v[20:21]
	v_cos_f32_e32 v13, v15
	v_sin_f32_e32 v15, v15
	v_cndmask_b32_e32 v21, v21, v29, vcc
	v_cndmask_b32_e32 v20, v20, v28, vcc
	v_cndmask_b32_e32 v19, v19, v31, vcc
	v_cndmask_b32_e32 v18, v18, v30, vcc
	v_pk_mul_f32 v[20:21], v[20:21], s[10:11] op_sel_hi:[1,0]
	v_pk_mul_f32 v[18:19], v[18:19], s[10:11] op_sel_hi:[1,0]
	v_cvt_pk_bf16_f32 v115, v20, v21
	s_waitcnt vmcnt(1)
	v_lshlrev_b32_e32 v20, 16, v0
	v_and_b32_e32 v21, 0xffff0000, v0
	v_cvt_pk_bf16_f32 v114, v18, v19
	s_waitcnt vmcnt(0)
	v_lshlrev_b32_e32 v18, 16, v4
	v_and_b32_e32 v19, 0xffff0000, v4
	v_pk_mul_f32 v[22:23], v[14:15], v[20:21]
	v_mul_f32_e32 v0, 0x3dcccccd, v11
	v_pk_fma_f32 v[22:23], v[12:13], v[18:19], v[22:23] neg_lo:[0,0,1] neg_hi:[0,0,1]
	v_pk_mul_f32 v[12:13], v[12:13], v[20:21]
	v_pk_mul_f32 v[34:35], v[34:35], s[10:11] op_sel_hi:[1,0]
	v_pk_fma_f32 v[12:13], v[14:15], v[18:19], v[12:13]
	v_mul_f32_e32 v0, 0.15915494, v0
	v_cndmask_b32_e32 v13, v13, v23, vcc
	v_cndmask_b32_e32 v12, v12, v22, vcc
	v_cvt_pk_bf16_f32 v110, v34, v35
	v_pk_mul_f32 v[34:35], v[12:13], s[10:11] op_sel_hi:[1,0]
	v_cos_f32_e32 v12, v0
	v_sin_f32_e32 v14, v0
	v_mul_f32_e32 v0, 0x3d0186e3, v11
	v_mul_f32_e32 v0, 0.15915494, v0
	v_cos_f32_e32 v13, v0
	v_sin_f32_e32 v15, v0
	v_lshlrev_b32_e32 v0, 16, v1
	v_and_b32_e32 v1, 0xffff0000, v1
	v_lshlrev_b32_e32 v4, 16, v5
	v_and_b32_e32 v5, 0xffff0000, v5
	v_pk_mul_f32 v[18:19], v[14:15], v[0:1]
	v_pk_mul_f32 v[0:1], v[12:13], v[0:1]
	v_pk_fma_f32 v[18:19], v[12:13], v[4:5], v[18:19] neg_lo:[0,0,1] neg_hi:[0,0,1]
	v_pk_fma_f32 v[0:1], v[14:15], v[4:5], v[0:1]
	v_mul_f32_e32 v4, 0x3c23d70b, v11
	v_pk_mul_f32 v[36:37], v[36:37], s[10:11] op_sel_hi:[1,0]
	v_mul_f32_e32 v5, 0.15915494, v4
	v_cvt_pk_bf16_f32 v104, v36, v37
	v_cos_f32_e32 v4, v5
	v_sin_f32_e32 v36, v5
	v_mul_f32_e32 v5, 0x3b4f3e39, v11
	v_mul_f32_e32 v37, 0.15915494, v5
	v_cos_f32_e32 v5, v37
	v_sin_f32_e32 v37, v37
	v_lshlrev_b32_e32 v22, 3, v8
	v_lshlrev_b32_e32 v52, 16, v2
	v_and_b32_e32 v53, 0xffff0000, v2
	v_pk_mul_f32 v[38:39], v[38:39], s[10:11] op_sel_hi:[1,0]
	v_pk_mul_f32 v[40:41], v[40:41], s[10:11] op_sel_hi:[1,0]
	v_ashrrev_i32_e32 v23, 31, v22
	v_add_u32_e32 v14, 0x1000, v22
	v_lshlrev_b32_e32 v50, 16, v6
	v_and_b32_e32 v51, 0xffff0000, v6
	v_pk_mul_f32 v[54:55], v[36:37], v[52:53]
	v_mul_f32_e32 v2, 0x3a831270, v11
	v_pk_mul_f32 v[42:43], v[42:43], s[10:11] op_sel_hi:[1,0]
	v_cvt_pk_bf16_f32 v106, v38, v39
	v_cvt_pk_bf16_f32 v100, v40, v41
	v_and_b32_e32 v38, 0x78, v22
	v_lshlrev_b64 v[40:41], 1, v[22:23]
	v_ashrrev_i32_e32 v15, 31, v14
	v_add_u32_e32 v22, 0x2000, v22
	v_pk_fma_f32 v[54:55], v[4:5], v[50:51], v[54:55] neg_lo:[0,0,1] neg_hi:[0,0,1]
	v_pk_mul_f32 v[4:5], v[4:5], v[52:53]
	v_mul_f32_e32 v2, 0.15915494, v2
	v_pk_mul_f32 v[44:45], v[44:45], s[10:11] op_sel_hi:[1,0]
	v_cvt_pk_bf16_f32 v102, v42, v43
	s_add_u32 s34, s19, s8
	v_lshlrev_b64 v[42:43], 1, v[14:15]
	v_ashrrev_i32_e32 v23, 31, v22
	v_pk_fma_f32 v[4:5], v[36:37], v[50:51], v[4:5]
	v_cos_f32_e32 v36, v2
	v_sin_f32_e32 v50, v2
	v_mul_f32_e32 v2, 0x39a5cb61, v11
	v_cvt_pk_bf16_f32 v96, v44, v45
	v_cndmask_b32_e32 v1, v1, v19, vcc
	v_cndmask_b32_e32 v0, v0, v18, vcc
	s_addc_u32 s35, s20, s2
	v_lshl_add_u64 v[12:13], s[16:17], 0, v[40:41]
	v_lshl_add_u64 v[18:19], s[16:17], 0, v[42:43]
	v_lshlrev_b64 v[44:45], 1, v[22:23]
	v_mul_f32_e32 v2, 0.15915494, v2
	v_ashrrev_i32_e32 v39, 4, v8
	global_load_dwordx4 v[12:15], v[12:13], off
	s_nop 0
	global_load_dwordx4 v[18:21], v[18:19], off
	v_lshl_add_u64 v[22:23], s[16:17], 0, v[44:45]
	v_mov_b64_e32 v[30:31], s[34:35]
	v_cos_f32_e32 v37, v2
	v_sin_f32_e32 v51, v2
	v_add_u32_e32 v17, 0x200, v8
	global_load_dwordx4 v[22:25], v[22:23], off
	v_mad_i64_i32 v[26:27], s[34:35], v39, s26, v[30:31]
	v_lshlrev_b32_e32 v142, 1, v38
	v_lshl_add_u64 v[46:47], v[26:27], 0, v[142:143]
	v_ashrrev_i32_e32 v56, 4, v17
	global_load_dwordx4 v[26:29], v[46:47], off
	v_mad_i64_i32 v[30:31], s[34:35], v56, s26, v[30:31]
	v_lshlrev_b32_e32 v2, 16, v3
	v_and_b32_e32 v3, 0xffff0000, v3
	v_pk_mul_f32 v[32:33], v[32:33], s[10:11] op_sel_hi:[1,0]
	v_lshl_add_u64 v[48:49], v[30:31], 0, v[142:143]
	v_lshlrev_b32_e32 v6, 16, v7
	v_and_b32_e32 v7, 0xffff0000, v7
	v_pk_mul_f32 v[52:53], v[50:51], v[2:3]
	v_pk_mul_f32 v[2:3], v[36:37], v[2:3]
	v_cvt_pk_bf16_f32 v108, v32, v33
	global_load_dwordx4 v[30:33], v[48:49], off
	v_pk_fma_f32 v[52:53], v[36:37], v[6:7], v[52:53] neg_lo:[0,0,1] neg_hi:[0,0,1]
	v_pk_fma_f32 v[2:3], v[50:51], v[6:7], v[2:3]
	v_pk_mul_f32 v[0:1], v[0:1], s[10:11] op_sel_hi:[1,0]
	v_cndmask_b32_e32 v3, v3, v53, vcc
	v_cndmask_b32_e32 v2, v2, v52, vcc
	s_add_u32 s16, s16, 0x6000
	v_cndmask_b32_e32 v5, v5, v55, vcc
	v_cndmask_b32_e32 v4, v4, v54, vcc
	v_pk_mul_f32 v[2:3], v[2:3], s[10:11] op_sel_hi:[1,0]
	v_cvt_pk_bf16_f32 v117, v0, v1
	v_mul_hi_i32 v0, v8, s25
	s_addc_u32 s17, s17, 0
	v_pk_mul_f32 v[4:5], v[4:5], s[10:11] op_sel_hi:[1,0]
	v_cvt_pk_bf16_f32 v119, v2, v3
	v_lshrrev_b32_e32 v1, 31, v0
	v_ashrrev_i32_e32 v0, 1, v0
	v_lshl_add_u64 v[2:3], s[16:17], 0, v[42:43]
	v_cvt_pk_bf16_f32 v118, v4, v5
	v_add3_u32 v6, v0, v1, v8
	v_lshl_add_u64 v[0:1], s[16:17], 0, v[40:41]
	v_lshl_add_u64 v[4:5], s[16:17], 0, v[44:45]
	global_load_dwordx4 v[120:123], v[2:3], off
	global_load_dwordx4 v[128:131], v[4:5], off
	global_load_dwordx4 v[132:135], v[46:47], off offset:256
	global_load_dwordx4 v[124:127], v[0:1], off
	global_load_dwordx4 v[136:139], v[48:49], off offset:256
	v_mul_hi_i32 v7, v17, s25
	v_add_u32_e32 v1, 0x400, v8
	v_lshrrev_b32_e32 v11, 31, v7
	v_ashrrev_i32_e32 v0, 1, v7
	v_mul_hi_i32 v2, v1, s25
	v_add3_u32 v0, v0, v11, v17
	v_lshrrev_b32_e32 v3, 31, v2
	v_ashrrev_i32_e32 v2, 1, v2
	v_lshlrev_b32_e32 v167, 3, v0
	v_add3_u32 v1, v2, v3, v1
	v_lshl_add_u32 v2, v6, 4, 0
	v_lshl_add_u32 v0, v0, 4, 0
	v_mad_u64_u32 v[146:147], s[16:17], v39, s27, v[38:39]
	v_mad_u64_u32 v[148:149], s[16:17], v56, s27, v[38:39]
	s_add_i32 s2, s1, s0
	s_mul_i32 s0, s2, 0x88000
	v_cmp_lt_i32_e32 vcc, v160, v161
	s_mul_hi_i32 s1, s2, 0x88000
	s_add_u32 s0, s0, 0xc1e6200
	s_addc_u32 s1, s1, 0
	v_lshlrev_b32_e32 v168, 3, v1
	v_lshlrev_b32_e32 v17, 2, v9
	v_lshlrev_b32_e32 v163, 3, v6
	v_mov_b32_e32 v3, v143
	v_mov_b32_e32 v4, v143
	v_mov_b32_e32 v5, v143
	v_mov_b32_e32 v6, v143
	v_mov_b32_e32 v7, v143
	v_mov_b32_e32 v9, v143
	v_mov_b32_e32 v11, v143
	s_waitcnt vmcnt(9)
	ds_write_b128 v2, v[12:15]
	s_waitcnt vmcnt(8)
	ds_write_b128 v0, v[18:21]
	v_lshl_add_u32 v0, v1, 4, 0
	v_lshlrev_b32_e32 v2, 4, v8
	v_mul_u32_u24_e32 v18, 0x68, v10
	v_mul_u32_u24_e32 v19, 0x84, v10
	v_and_b32_e32 v2, 0xf0, v2
	s_waitcnt vmcnt(7)
	ds_write_b128 v0, v[22:25]
	v_lshl_add_u32 v0, v146, 1, 0
	v_add_u32_e32 v0, 0x6800, v0
	v_mov_b32_e32 v14, v143
	v_mov_b32_e32 v15, v143
	v_mov_b32_e32 v8, v143
	s_waitcnt vmcnt(6)
	ds_write2_b64 v0, v[26:27], v[28:29] offset1:1
	v_lshl_add_u32 v0, v148, 1, 0
	v_add_u32_e32 v0, 0x6800, v0
	v_mov_b32_e32 v10, v143
	v_mov_b32_e32 v12, v143
	v_mov_b32_e32 v13, v143
	v_lshlrev_b32_e32 v170, 1, v18
	v_lshlrev_b32_e32 v142, 1, v17
	v_lshlrev_b32_e32 v162, 1, v19
	v_cvt_pk_bf16_f32 v116, v34, v35
	v_mov_b32_e32 v149, 0
	s_waitcnt vmcnt(5)
	ds_write2_b64 v0, v[30:31], v[32:33] offset1:1
	v_cndmask_b32_e32 v0, v165, v160, vcc
	v_lshlrev_b32_e32 v147, 2, v0
	v_mov_b64_e32 v[0:1], s[0:1]
	v_mad_i64_i32 v[150:151], s[0:1], v56, s26, v[0:1]
	v_mad_i64_i32 v[152:153], s[0:1], v39, s26, v[0:1]
	s_mul_hi_i32 s1, s2, 0xcc000
	s_mul_i32 s2, s2, 0xcc000
	s_add_u32 s0, s2, 0xb532000
	v_or_b32_e32 v150, v150, v2
	v_or_b32_e32 v152, v152, v2
	s_addc_u32 s1, s1, 0
	v_mov_b32_e32 v0, v143
	v_mov_b32_e32 v1, v143
	v_mov_b32_e32 v2, v143
	v_mov_b64_e32 v[30:31], v[14:15]
	v_lshl_add_u64 v[154:155], s[0:1], 0, v[40:41]
	v_lshl_add_u64 v[156:157], s[0:1], 0, v[42:43]
	v_lshl_add_u64 v[158:159], s[0:1], 0, v[44:45]
	v_mov_b64_e32 v[28:29], v[12:13]
	v_mov_b64_e32 v[26:27], v[10:11]
	v_mov_b64_e32 v[24:25], v[8:9]
	v_mov_b64_e32 v[22:23], v[6:7]
	v_mov_b64_e32 v[20:21], v[4:5]
	v_mov_b64_e32 v[18:19], v[2:3]
	v_mov_b64_e32 v[16:17], v[0:1]
	s_mov_b32 s1, 0
	s_waitcnt lgkmcnt(0)
	s_barrier
	s_mov_b32 s98, 0
	s_mov_b32 s99, 0xaa00
	s_cmp_eq_u32 s100, 0
	s_cbranch_scc1 .Latt0_nostag
	s_barrier
.Latt0_nostag:
.LBB0_663:
	s_add_i32 s0, s1, 1
	s_mov_b32 s2, s99
	v_lshl_add_u32 v32, v163, 1, s2
	s_waitcnt vmcnt(1)
	ds_write_b128 v32, v[124:127]
	v_lshl_add_u32 v32, v167, 1, s2
	ds_write_b128 v32, v[120:123]
	v_lshl_add_u32 v32, v168, 1, s2
	ds_write_b128 v32, v[128:131]
	v_lshl_add_u32 v32, v146, 1, s2
	v_add_u32_e32 v32, 0x6800, v32
	ds_write2_b64 v32, v[132:133], v[134:135] offset1:1
	v_lshl_add_u32 v32, v148, 1, s2
	v_add_u32_e32 v32, 0x6800, v32
	s_cmp_gt_u32 s1, 31
	s_waitcnt vmcnt(0)
	ds_write2_b64 v32, v[136:137], v[138:139] offset1:1
	s_cbranch_scc1 .LBB0_665
	v_lshl_add_u64 v[32:33], s[4:5], 0, v[154:155]
	v_lshl_add_u64 v[34:35], s[4:5], 0, v[156:157]
	global_load_dwordx4 v[124:127], v[32:33], off
	global_load_dwordx4 v[120:123], v[34:35], off
	v_lshl_add_u64 v[32:33], s[4:5], 0, v[158:159]
	v_lshl_add_u64 v[34:35], s[4:5], 0, v[152:153]
	global_load_dwordx4 v[128:131], v[32:33], off
	global_load_dwordx4 v[132:135], v[34:35], off
	v_lshl_add_u64 v[32:33], s[4:5], 0, v[150:151]
	global_load_dwordx4 v[136:139], v[32:33], off
.LBB0_665:
	s_mov_b32 s1, s98
	v_add3_u32 v171, s1, v169, v170
	ds_read_b128 v[32:35], v171
	ds_read_b128 v[174:177], v171 offset:32
	s_waitcnt lgkmcnt(1)
	v_mfma_f32_32x32x16_bf16 v[80:95], v[32:35], v[108:111], 0
	ds_read_b128 v[32:35], v171 offset:6656
	ds_read_b128 v[178:181], v171 offset:6688
	s_waitcnt lgkmcnt(1)
	v_mfma_f32_32x32x16_bf16 v[64:79], v[32:35], v[108:111], 0
	ds_read_b128 v[32:35], v171 offset:13312
	ds_read_b128 v[182:185], v171 offset:13344
	s_waitcnt lgkmcnt(1)
	v_mfma_f32_32x32x16_bf16 v[48:63], v[32:35], v[108:111], 0
	ds_read_b128 v[32:35], v171 offset:19968
	ds_read_b128 v[186:189], v171 offset:20000
	v_mfma_f32_32x32x16_bf16 v[80:95], v[174:177], v[104:107], v[80:95]
	s_waitcnt lgkmcnt(1)
	v_mfma_f32_32x32x16_bf16 v[32:47], v[32:35], v[108:111], 0
	v_mfma_f32_32x32x16_bf16 v[64:79], v[178:181], v[104:107], v[64:79]
	ds_read_b128 v[174:177], v171 offset:64
	ds_read_b128 v[178:181], v171 offset:96
	v_mfma_f32_32x32x16_bf16 v[48:63], v[182:185], v[104:107], v[48:63]
	s_waitcnt lgkmcnt(1)
	v_mfma_f32_32x32x16_bf16 v[80:95], v[174:177], v[100:103], v[80:95]
	ds_read_b128 v[174:177], v171 offset:6720
	ds_read_b128 v[182:185], v171 offset:6752
	v_mfma_f32_32x32x16_bf16 v[32:47], v[186:189], v[104:107], v[32:47]
	s_waitcnt lgkmcnt(1)
	v_mfma_f32_32x32x16_bf16 v[64:79], v[174:177], v[100:103], v[64:79]
	ds_read_b128 v[174:177], v171 offset:13376
	ds_read_b128 v[186:189], v171 offset:13408
	s_waitcnt lgkmcnt(1)
	v_mfma_f32_32x32x16_bf16 v[48:63], v[174:177], v[100:103], v[48:63]
	ds_read_b128 v[174:177], v171 offset:20032
	ds_read_b128 v[190:193], v171 offset:20064
	v_mfma_f32_32x32x16_bf16 v[80:95], v[178:181], v[96:99], v[80:95]
	s_waitcnt lgkmcnt(1)
	v_mfma_f32_32x32x16_bf16 v[32:47], v[174:177], v[100:103], v[32:47]
	ds_read_b128 v[174:177], v171 offset:128
	ds_read_b128 v[178:181], v171 offset:160
	s_waitcnt lgkmcnt(1)
	v_mfma_f32_32x32x16_bf16 v[80:95], v[174:177], v[112:115], v[80:95]
	v_mfma_f32_32x32x16_bf16 v[64:79], v[182:185], v[96:99], v[64:79]
	ds_read_b128 v[174:177], v171 offset:6784
	ds_read_b128 v[182:185], v171 offset:6816
	v_mfma_f32_32x32x16_bf16 v[48:63], v[186:189], v[96:99], v[48:63]
	s_waitcnt lgkmcnt(2)
	v_mfma_f32_32x32x16_bf16 v[80:95], v[178:181], v[116:119], v[80:95]
	s_waitcnt lgkmcnt(1)
	v_mfma_f32_32x32x16_bf16 v[64:79], v[174:177], v[112:115], v[64:79]
	ds_read_b128 v[174:177], v171 offset:13440
	ds_read_b128 v[186:189], v171 offset:13472
	s_nop 7
	v_max_f32_e32 v173, v80, v80
	s_waitcnt lgkmcnt(1)
	v_mfma_f32_32x32x16_bf16 v[48:63], v[174:177], v[112:115], v[48:63]
	ds_read_b128 v[174:177], v171 offset:20096
	ds_read_b128 v[178:181], v171 offset:20128
	v_max_f32_e32 v171, v81, v81
	v_max_f32_e32 v171, v173, v171
	v_max3_f32 v171, v171, v82, v83
	v_max3_f32 v171, v171, v84, v85
	v_max3_f32 v171, v171, v86, v87
	v_max3_f32 v171, v171, v88, v89
	v_mfma_f32_32x32x16_bf16 v[32:47], v[190:193], v[96:99], v[32:47]
	v_max3_f32 v171, v171, v90, v91
	v_max3_f32 v171, v171, v92, v93
	v_max3_f32 v171, v171, v94, v95
	v_mfma_f32_32x32x16_bf16 v[64:79], v[182:185], v[116:119], v[64:79]
	s_waitcnt lgkmcnt(2)
	v_mfma_f32_32x32x16_bf16 v[48:63], v[186:189], v[116:119], v[48:63]
	s_nop 9
	v_max3_f32 v171, v171, v64, v65
	v_max3_f32 v171, v171, v66, v67
	v_max3_f32 v171, v171, v68, v69
	v_max3_f32 v171, v171, v70, v71
	v_max3_f32 v171, v171, v72, v73
	v_max3_f32 v171, v171, v74, v75
	v_max3_f32 v171, v171, v76, v77
	s_waitcnt lgkmcnt(1)
	v_mfma_f32_32x32x16_bf16 v[32:47], v[174:177], v[112:115], v[32:47]
	v_max3_f32 v171, v171, v78, v79
	v_max3_f32 v171, v171, v48, v49
	v_max3_f32 v171, v171, v50, v51
	v_max3_f32 v171, v171, v52, v53
	v_max3_f32 v171, v171, v54, v55
	v_max3_f32 v171, v171, v56, v57
	v_max3_f32 v171, v171, v58, v59
	s_waitcnt lgkmcnt(0)
	v_mfma_f32_32x32x16_bf16 v[32:47], v[178:181], v[116:119], v[32:47]
	v_max3_f32 v171, v171, v60, v61
	v_max3_f32 v171, v171, v62, v63
	s_nop 9
	v_max3_f32 v171, v171, v32, v33
	v_max3_f32 v171, v171, v34, v35
	v_max3_f32 v171, v171, v36, v37
	v_max3_f32 v171, v171, v38, v39
	v_max3_f32 v171, v171, v40, v41
	v_max3_f32 v171, v171, v42, v43
	v_max3_f32 v171, v171, v44, v45
	v_max3_f32 v171, v171, v46, v47
	ds_bpermute_b32 v173, v147, v171
	s_waitcnt lgkmcnt(0)
	v_max3_f32 v171, v172, v171, v173
	v_cmp_gt_f32_e32 vcc, v171, v172
	s_cbranch_vccz .LBB0_667
	v_sub_f32_e32 v172, v172, v171
	v_exp_f32_e32 v172, v172
	s_nop 0
	v_pk_mul_f32 v[30:31], v[30:31], v[172:173] op_sel_hi:[1,0]
	v_pk_mul_f32 v[28:29], v[28:29], v[172:173] op_sel_hi:[1,0]
	v_pk_mul_f32 v[26:27], v[26:27], v[172:173] op_sel_hi:[1,0]
	v_pk_mul_f32 v[24:25], v[24:25], v[172:173] op_sel_hi:[1,0]
	v_pk_mul_f32 v[22:23], v[22:23], v[172:173] op_sel_hi:[1,0]
	v_pk_mul_f32 v[20:21], v[20:21], v[172:173] op_sel_hi:[1,0]
	v_pk_mul_f32 v[18:19], v[18:19], v[172:173] op_sel_hi:[1,0]
	v_pk_mul_f32 v[16:17], v[16:17], v[172:173] op_sel_hi:[1,0]
	v_pk_mul_f32 v[14:15], v[14:15], v[172:173] op_sel_hi:[1,0]
	v_pk_mul_f32 v[12:13], v[12:13], v[172:173] op_sel_hi:[1,0]
	v_pk_mul_f32 v[10:11], v[10:11], v[172:173] op_sel_hi:[1,0]
	v_pk_mul_f32 v[8:9], v[8:9], v[172:173] op_sel_hi:[1,0]
	v_pk_mul_f32 v[6:7], v[6:7], v[172:173] op_sel_hi:[1,0]
	v_pk_mul_f32 v[4:5], v[4:5], v[172:173] op_sel_hi:[1,0]
	v_pk_mul_f32 v[2:3], v[2:3], v[172:173] op_sel_hi:[1,0]
	v_pk_mul_f32 v[0:1], v[0:1], v[172:173] op_sel_hi:[1,0]
	v_mul_f32_e32 v149, v149, v172
	s_branch .LBB0_668

.LBB0_668:
	s_waitcnt lgkmcnt(0)
	s_barrier
	v_sub_f32_e32 v80, v80, v171
	v_exp_f32_e32 v80, v80
	v_sub_f32_e32 v81, v81, v171
	v_exp_f32_e32 v81, v81
	v_sub_f32_e32 v82, v82, v171
	v_exp_f32_e32 v82, v82
	v_sub_f32_e32 v83, v83, v171
	v_exp_f32_e32 v83, v83
	v_sub_f32_e32 v84, v84, v171
	v_add_f32_e32 v172, 0, v80
	v_exp_f32_e32 v84, v84
	v_sub_f32_e32 v85, v85, v171
	v_add_f32_e32 v172, v81, v172
	v_exp_f32_e32 v85, v85
	v_sub_f32_e32 v86, v86, v171
	v_add_f32_e32 v172, v82, v172
	v_exp_f32_e32 v86, v86
	v_sub_f32_e32 v87, v87, v171
	v_add_f32_e32 v172, v83, v172
	v_exp_f32_e32 v87, v87
	v_sub_f32_e32 v88, v88, v171
	v_add_f32_e32 v172, v84, v172
	v_exp_f32_e32 v88, v88
	v_sub_f32_e32 v89, v89, v171
	v_add_f32_e32 v172, v85, v172
	v_exp_f32_e32 v89, v89
	v_sub_f32_e32 v90, v90, v171
	v_add_f32_e32 v172, v86, v172
	v_exp_f32_e32 v90, v90
	v_sub_f32_e32 v91, v91, v171
	v_add_f32_e32 v172, v87, v172
	v_exp_f32_e32 v91, v91
	v_sub_f32_e32 v92, v92, v171
	v_add_f32_e32 v172, v88, v172
	v_exp_f32_e32 v92, v92
	v_sub_f32_e32 v93, v93, v171
	v_add_f32_e32 v172, v89, v172
	v_exp_f32_e32 v93, v93
	v_sub_f32_e32 v94, v94, v171
	v_add_f32_e32 v172, v90, v172
	v_exp_f32_e32 v94, v94
	v_sub_f32_e32 v95, v95, v171
	v_add_f32_e32 v172, v91, v172
	v_exp_f32_e32 v95, v95
	v_sub_f32_e32 v64, v64, v171
	v_add_f32_e32 v172, v92, v172
	v_exp_f32_e32 v173, v64
	v_sub_f32_e32 v64, v65, v171
	v_add_f32_e32 v172, v93, v172
	v_exp_f32_e32 v174, v64
	v_sub_f32_e32 v64, v66, v171
	v_add_f32_e32 v172, v94, v172
	v_exp_f32_e32 v175, v64
	v_sub_f32_e32 v65, v67, v171
	v_add_f32_e32 v64, v95, v172
	v_exp_f32_e32 v172, v65
	v_sub_f32_e32 v65, v68, v171
	v_add_f32_e32 v64, v173, v64
	v_exp_f32_e32 v176, v65
	v_sub_f32_e32 v65, v69, v171
	v_add_f32_e32 v64, v174, v64
	v_exp_f32_e32 v177, v65
	v_sub_f32_e32 v65, v70, v171
	v_add_f32_e32 v64, v175, v64
	v_exp_f32_e32 v178, v65
	v_sub_f32_e32 v65, v71, v171
	v_add_f32_e32 v64, v172, v64
	v_exp_f32_e32 v179, v65
	v_sub_f32_e32 v65, v72, v171
	v_add_f32_e32 v64, v176, v64
	v_exp_f32_e32 v72, v65
	v_sub_f32_e32 v65, v73, v171
	v_add_f32_e32 v64, v177, v64
	v_exp_f32_e32 v73, v65
	v_sub_f32_e32 v65, v74, v171
	v_add_f32_e32 v64, v178, v64
	v_exp_f32_e32 v74, v65
	v_sub_f32_e32 v65, v75, v171
	v_add_f32_e32 v64, v179, v64
	v_exp_f32_e32 v75, v65
	v_sub_f32_e32 v65, v76, v171
	v_add_f32_e32 v64, v72, v64
	v_exp_f32_e32 v76, v65
	v_sub_f32_e32 v65, v77, v171
	v_add_f32_e32 v64, v73, v64
	v_exp_f32_e32 v77, v65
	v_sub_f32_e32 v65, v78, v171
	v_add_f32_e32 v64, v74, v64
	v_exp_f32_e32 v78, v65
	v_sub_f32_e32 v65, v79, v171
	v_add_f32_e32 v64, v75, v64
	v_exp_f32_e32 v79, v65
	v_sub_f32_e32 v48, v48, v171
	v_add_f32_e32 v64, v76, v64
	v_exp_f32_e32 v180, v48
	v_sub_f32_e32 v48, v49, v171
	v_add_f32_e32 v64, v77, v64
	v_exp_f32_e32 v181, v48
	v_sub_f32_e32 v48, v50, v171
	v_add_f32_e32 v64, v78, v64
	v_exp_f32_e32 v182, v48
	v_add_f32_e32 v48, v79, v64
	v_add_f32_e32 v48, v180, v48
	v_add_f32_e32 v48, v181, v48
	v_add_f32_e32 v183, v182, v48
	v_sub_f32_e32 v48, v51, v171
	v_exp_f32_e32 v184, v48
	v_sub_f32_e32 v48, v52, v171
	v_add3_u32 v52, s1, v142, v162
	v_exp_f32_e32 v185, v48
	v_sub_f32_e32 v48, v53, v171
	v_add_u32_e32 v187, 0x6800, v52
	v_exp_f32_e32 v186, v48
	ds_read2_b64 v[48:51], v187 offset1:2
	v_sub_f32_e32 v53, v54, v171
	v_exp_f32_e32 v188, v53
	v_cvt_pk_bf16_f32 v64, v80, v81
	v_cvt_pk_bf16_f32 v65, v82, v83
	v_cvt_pk_bf16_f32 v66, v84, v85
	v_cvt_pk_bf16_f32 v67, v86, v87
	v_add_u32_e32 v80, 0x8800, v52
	ds_read2_b64 v[68:71], v80 offset0:32 offset1:34
	s_waitcnt lgkmcnt(1)
	v_mfma_f32_32x32x16_bf16 v[16:31], v[48:51], v[64:67], v[16:31]
	v_add_f32_e32 v48, v184, v183
	v_add_f32_e32 v48, v185, v48
	v_add_f32_e32 v48, v186, v48
	v_add_f32_e32 v81, v188, v48
	v_sub_f32_e32 v48, v55, v171
	v_exp_f32_e32 v82, v48
	ds_read2_b64 v[48:51], v187 offset0:4 offset1:6
	v_sub_f32_e32 v52, v56, v171
	s_waitcnt lgkmcnt(1)
	v_mfma_f32_32x32x16_bf16 v[0:15], v[68:71], v[64:67], v[0:15]
	v_exp_f32_e32 v68, v52
	v_cvt_pk_bf16_f32 v52, v88, v89
	v_cvt_pk_bf16_f32 v53, v90, v91
	v_cvt_pk_bf16_f32 v54, v92, v93
	v_cvt_pk_bf16_f32 v55, v94, v95
	ds_read2_b64 v[64:67], v80 offset0:36 offset1:38
	v_sub_f32_e32 v32, v32, v171
	s_waitcnt lgkmcnt(1)
	v_mfma_f32_32x32x16_bf16 v[16:31], v[48:51], v[52:55], v[16:31]
	v_add_f32_e32 v48, v82, v81
	v_add_f32_e32 v69, v68, v48
	v_sub_f32_e32 v48, v57, v171
	v_exp_f32_e32 v70, v48
	v_sub_f32_e32 v48, v58, v171
	v_exp_f32_e32 v71, v48
	ds_read2_b64 v[48:51], v187 offset0:8 offset1:10
	s_waitcnt lgkmcnt(1)
	v_mfma_f32_32x32x16_bf16 v[0:15], v[64:67], v[52:55], v[0:15]
	v_sub_f32_e32 v52, v59, v171
	ds_read2_b64 v[56:59], v80 offset0:40 offset1:42
	v_exp_f32_e32 v64, v52
	v_cvt_pk_bf16_f32 v52, v173, v174
	v_cvt_pk_bf16_f32 v53, v175, v172
	v_cvt_pk_bf16_f32 v54, v176, v177
	v_cvt_pk_bf16_f32 v55, v178, v179
	v_exp_f32_e32 v65, v32
	v_sub_f32_e32 v32, v33, v171
	s_waitcnt lgkmcnt(1)
	v_mfma_f32_32x32x16_bf16 v[16:31], v[48:51], v[52:55], v[16:31]
	v_sub_f32_e32 v48, v60, v171
	v_exp_f32_e32 v60, v48
	v_sub_f32_e32 v48, v61, v171
	v_exp_f32_e32 v61, v48
	v_sub_f32_e32 v48, v62, v171
	v_exp_f32_e32 v62, v48
	ds_read2_b64 v[48:51], v187 offset0:12 offset1:14
	s_waitcnt lgkmcnt(1)
	v_mfma_f32_32x32x16_bf16 v[0:15], v[56:59], v[52:55], v[0:15]
	ds_read2_b64 v[56:59], v80 offset0:44 offset1:46
	v_sub_f32_e32 v52, v63, v171
	v_exp_f32_e32 v63, v52
	v_cvt_pk_bf16_f32 v52, v72, v73
	v_cvt_pk_bf16_f32 v53, v74, v75
	v_cvt_pk_bf16_f32 v54, v76, v77
	v_cvt_pk_bf16_f32 v55, v78, v79
	v_exp_f32_e32 v66, v32
	v_sub_f32_e32 v32, v34, v171
	s_waitcnt lgkmcnt(1)
	v_mfma_f32_32x32x16_bf16 v[16:31], v[48:51], v[52:55], v[16:31]
	ds_read2_b64 v[48:51], v187 offset0:16 offset1:18
	v_exp_f32_e32 v67, v32
	v_sub_f32_e32 v32, v35, v171
	v_cvt_pk_bf16_f32 v33, v182, v184
	v_cvt_pk_bf16_f32 v34, v185, v186
	v_cvt_pk_bf16_f32 v35, v188, v82
	v_sub_f32_e32 v36, v36, v171
	s_waitcnt lgkmcnt(1)
	v_mfma_f32_32x32x16_bf16 v[0:15], v[56:59], v[52:55], v[0:15]
	ds_read2_b64 v[52:55], v80 offset0:48 offset1:50
	v_exp_f32_e32 v56, v32
	v_cvt_pk_bf16_f32 v32, v180, v181
	v_exp_f32_e32 v57, v36
	v_sub_f32_e32 v36, v37, v171
	v_exp_f32_e32 v58, v36
	v_sub_f32_e32 v36, v38, v171
	s_waitcnt lgkmcnt(1)
	v_mfma_f32_32x32x16_bf16 v[16:31], v[48:51], v[32:35], v[16:31]
	ds_read2_b64 v[48:51], v187 offset0:20 offset1:22
	v_exp_f32_e32 v59, v36
	v_sub_f32_e32 v40, v40, v171
	v_lshl_add_u64 v[150:151], v[150:151], 0, s[14:15]
	v_lshl_add_u64 v[152:153], v[152:153], 0, s[14:15]
	v_lshl_add_u64 v[154:155], v[154:155], 0, s[12:13]
	v_lshl_add_u64 v[156:157], v[156:157], 0, s[12:13]
	s_waitcnt lgkmcnt(1)
	v_mfma_f32_32x32x16_bf16 v[0:15], v[52:55], v[32:35], v[0:15]
	v_sub_f32_e32 v32, v39, v171
	ds_read2_b64 v[36:39], v80 offset0:52 offset1:54
	v_exp_f32_e32 v52, v32
	v_cvt_pk_bf16_f32 v32, v68, v70
	v_cvt_pk_bf16_f32 v33, v71, v64
	v_cvt_pk_bf16_f32 v34, v60, v61
	v_cvt_pk_bf16_f32 v35, v62, v63
	v_exp_f32_e32 v53, v40
	v_sub_f32_e32 v40, v41, v171
	s_waitcnt lgkmcnt(1)
	v_mfma_f32_32x32x16_bf16 v[16:31], v[48:51], v[32:35], v[16:31]
	ds_read2_b64 v[48:51], v187 offset0:24 offset1:26
	v_exp_f32_e32 v54, v40
	v_sub_f32_e32 v40, v42, v171
	v_exp_f32_e32 v55, v40
	v_sub_f32_e32 v40, v44, v171
	v_exp_f32_e32 v44, v40
	v_sub_f32_e32 v40, v45, v171
	s_waitcnt lgkmcnt(1)
	v_mfma_f32_32x32x16_bf16 v[0:15], v[36:39], v[32:35], v[0:15]
	ds_read2_b64 v[36:39], v80 offset0:56 offset1:58
	v_sub_f32_e32 v32, v43, v171
	v_exp_f32_e32 v45, v40
	v_sub_f32_e32 v40, v46, v171
	v_exp_f32_e32 v68, v32
	v_cvt_pk_bf16_f32 v32, v65, v66
	v_cvt_pk_bf16_f32 v33, v67, v56
	v_cvt_pk_bf16_f32 v34, v57, v58
	v_cvt_pk_bf16_f32 v35, v59, v52
	v_exp_f32_e32 v46, v40
	ds_read2_b64 v[40:43], v187 offset0:28 offset1:30
	s_waitcnt lgkmcnt(2)
	v_mfma_f32_32x32x16_bf16 v[16:31], v[48:51], v[32:35], v[16:31]
	s_cmp_lg_u32 s0, 33
	v_lshl_add_u64 v[158:159], v[158:159], 0, s[12:13]
	s_waitcnt lgkmcnt(1)
	v_mfma_f32_32x32x16_bf16 v[0:15], v[36:39], v[32:35], v[0:15]
	v_sub_f32_e32 v32, v47, v171
	v_exp_f32_e32 v47, v32
	ds_read2_b64 v[36:39], v80 offset0:60 offset1:62
	v_cvt_pk_bf16_f32 v32, v53, v54
	v_cvt_pk_bf16_f32 v33, v55, v68
	v_cvt_pk_bf16_f32 v34, v44, v45
	v_cvt_pk_bf16_f32 v35, v46, v47
	s_waitcnt lgkmcnt(0)
	s_barrier
	v_mfma_f32_32x32x16_bf16 v[16:31], v[40:43], v[32:35], v[16:31]
	v_add_f32_e32 v40, v70, v69
	v_add_f32_e32 v40, v71, v40
	v_add_f32_e32 v40, v64, v40
	v_add_f32_e32 v40, v60, v40
	v_add_f32_e32 v40, v61, v40
	v_add_f32_e32 v40, v62, v40
	v_add_f32_e32 v40, v63, v40
	v_mfma_f32_32x32x16_bf16 v[0:15], v[36:39], v[32:35], v[0:15]
	v_add_f32_e32 v32, v65, v40
	v_add_f32_e32 v32, v66, v32
	v_add_f32_e32 v32, v67, v32
	v_add_f32_e32 v32, v56, v32
	v_add_f32_e32 v32, v57, v32
	v_add_f32_e32 v32, v58, v32
	v_add_f32_e32 v32, v59, v32
	v_add_f32_e32 v32, v52, v32
	v_add_f32_e32 v32, v53, v32
	v_add_f32_e32 v32, v54, v32
	v_add_f32_e32 v32, v55, v32
	v_add_f32_e32 v32, v68, v32
	v_add_f32_e32 v32, v44, v32
	v_add_f32_e32 v32, v45, v32
	v_add_f32_e32 v32, v46, v32
	v_add_f32_e32 v32, v47, v32
	v_add_f32_e32 v149, v149, v32
	s_cbranch_scc0 .LBB0_659
	v_mov_b32_e32 v172, v171
	s_mov_b32 s1, s0
	s_mov_b32 s98, s99
	s_add_i32 s99, s99, 0xaa00
	s_cmp_lt_u32 s99, 0x1fe00
	s_cselect_b32 s99, s99, 0
	s_branch .LBB0_663

.LBB0_2121:
	s_or_b64 exec, exec, s[44:45]
	s_mov_b64 s[0:1], s[92:93]
	s_waitcnt lgkmcnt(0)
	s_barrier
	s_load_dwordx2 s[6:7], s[0:1], 0xd0
	v_readlane_b32 s0, v255, 21
	v_readlane_b32 s1, v255, 22
	s_andn2_b64 vcc, exec, s[0:1]
	v_readlane_b32 s2, v255, 8
	s_cbranch_vccnz .LBB0_2135
	s_waitcnt lgkmcnt(0)
	s_add_u32 s4, s6, 0xa866000
	s_addc_u32 s5, s7, 0
	s_add_u32 s0, s6, 0xb526000
	s_addc_u32 s1, s7, 0
	s_add_u32 s13, s6, 0xc1e6000
	s_addc_u32 s20, s7, 0
	s_add_u32 s8, s6, 0x32dc000
	v_and_b32_e32 v0, 64, v165
	s_addc_u32 s9, s7, 0
	s_movk_i32 s21, 0xffe0
	s_movk_i32 s24, 0x300
	v_mov_b64_e32 v[140:141], s[4:5]
	s_mov_b32 s11, 0
	v_mov_b32_e32 v143, 0
	s_mov_b32 s12, 0x3e16c740
	s_mov_b32 s25, 0x2aaaaaab
	s_movk_i32 s26, 0x2200
	s_movk_i32 s27, 0x84
	s_mov_b64 s[14:15], 0x6000
	s_mov_b64 s[16:17], 0x100
	s_add_i32 s28, 0, 0x6800
	v_readfirstlane_b32 s100, v164
	s_nop 3
	s_lshr_b32 s100, s100, 8
	v_xor_b32_e32 v160, 32, v165
	v_add_u32_e32 v161, 64, v0
	v_readlane_b32 s29, v255, 0
	s_branch .LBB0_2126

.LBB0_2125:
	s_waitcnt lgkmcnt(0)
	s_barrier
	v_sub_f32_e32 v80, v80, v96
	v_exp_f32_e32 v80, v80
	v_sub_f32_e32 v81, v81, v96
	v_sub_f32_e32 v82, v82, v96
	v_exp_f32_e32 v81, v81
	v_exp_f32_e32 v82, v82
	v_sub_f32_e32 v83, v83, v96
	v_exp_f32_e32 v83, v83
	v_sub_f32_e32 v84, v84, v96
	v_add_f32_e32 v97, 0, v80
	v_exp_f32_e32 v84, v84
	v_sub_f32_e32 v85, v85, v96
	v_add_f32_e32 v97, v81, v97
	v_exp_f32_e32 v85, v85
	v_sub_f32_e32 v86, v86, v96
	v_add_f32_e32 v97, v82, v97
	v_exp_f32_e32 v86, v86
	v_sub_f32_e32 v87, v87, v96
	v_add_f32_e32 v97, v83, v97
	v_exp_f32_e32 v87, v87
	v_sub_f32_e32 v88, v88, v96
	v_add_f32_e32 v97, v84, v97
	v_exp_f32_e32 v88, v88
	v_sub_f32_e32 v89, v89, v96
	v_add_f32_e32 v97, v85, v97
	v_exp_f32_e32 v89, v89
	v_sub_f32_e32 v90, v90, v96
	v_add_f32_e32 v97, v86, v97
	v_exp_f32_e32 v90, v90
	v_sub_f32_e32 v91, v91, v96
	v_add_f32_e32 v97, v87, v97
	v_exp_f32_e32 v91, v91
	v_sub_f32_e32 v92, v92, v96
	v_add_f32_e32 v97, v88, v97
	v_exp_f32_e32 v92, v92
	v_sub_f32_e32 v93, v93, v96
	v_add_f32_e32 v97, v89, v97
	v_exp_f32_e32 v93, v93
	v_sub_f32_e32 v94, v94, v96
	v_add_f32_e32 v97, v90, v97
	v_exp_f32_e32 v94, v94
	v_sub_f32_e32 v95, v95, v96
	v_add_f32_e32 v97, v91, v97
	v_exp_f32_e32 v95, v95
	v_sub_f32_e32 v64, v64, v96
	v_add_f32_e32 v97, v92, v97
	v_exp_f32_e32 v98, v64
	v_sub_f32_e32 v65, v65, v96
	v_add_f32_e32 v64, v93, v97
	v_exp_f32_e32 v97, v65
	v_sub_f32_e32 v65, v66, v96
	v_add_f32_e32 v64, v94, v64
	v_exp_f32_e32 v99, v65
	v_sub_f32_e32 v65, v67, v96
	v_add_f32_e32 v64, v95, v64
	v_exp_f32_e32 v100, v65
	v_sub_f32_e32 v65, v68, v96
	v_add_f32_e32 v64, v98, v64
	v_exp_f32_e32 v68, v65
	v_sub_f32_e32 v65, v69, v96
	v_add_f32_e32 v64, v97, v64
	v_exp_f32_e32 v69, v65
	v_sub_f32_e32 v65, v70, v96
	v_add_f32_e32 v64, v99, v64
	v_exp_f32_e32 v70, v65
	v_sub_f32_e32 v65, v71, v96
	v_add_f32_e32 v64, v100, v64
	v_exp_f32_e32 v71, v65
	v_sub_f32_e32 v65, v72, v96
	v_add_f32_e32 v64, v68, v64
	v_exp_f32_e32 v72, v65
	v_sub_f32_e32 v65, v73, v96
	v_add_f32_e32 v64, v69, v64
	v_exp_f32_e32 v73, v65
	v_sub_f32_e32 v65, v74, v96
	v_add_f32_e32 v64, v70, v64
	v_exp_f32_e32 v74, v65
	v_sub_f32_e32 v65, v75, v96
	v_add_f32_e32 v64, v71, v64
	v_exp_f32_e32 v75, v65
	v_sub_f32_e32 v65, v76, v96
	v_add_f32_e32 v64, v72, v64
	v_exp_f32_e32 v76, v65
	v_sub_f32_e32 v65, v77, v96
	v_add_f32_e32 v64, v73, v64
	v_exp_f32_e32 v77, v65
	v_sub_f32_e32 v65, v78, v96
	v_add_f32_e32 v64, v74, v64
	v_exp_f32_e32 v78, v65
	v_sub_f32_e32 v65, v79, v96
	v_add_f32_e32 v64, v75, v64
	v_exp_f32_e32 v79, v65
	v_sub_f32_e32 v48, v48, v96
	v_add_f32_e32 v64, v76, v64
	v_exp_f32_e32 v101, v48
	v_sub_f32_e32 v49, v49, v96
	v_add_f32_e32 v48, v77, v64
	v_exp_f32_e32 v102, v49
	v_sub_f32_e32 v49, v50, v96
	v_add_f32_e32 v48, v78, v48
	v_exp_f32_e32 v103, v49
	v_sub_f32_e32 v49, v51, v96
	v_add_f32_e32 v48, v79, v48
	v_exp_f32_e32 v104, v49
	v_sub_f32_e32 v49, v52, v96
	v_add_f32_e32 v48, v101, v48
	v_exp_f32_e32 v105, v49
	v_add_f32_e32 v48, v102, v48
	v_add_f32_e32 v48, v103, v48
	v_add_f32_e32 v48, v104, v48
	v_add_f32_e32 v106, v105, v48
	v_sub_f32_e32 v48, v53, v96
	v_exp_f32_e32 v107, v48
	v_sub_f32_e32 v48, v54, v96
	v_exp_f32_e32 v108, v48
	v_sub_f32_e32 v48, v55, v96
	v_add3_u32 v110, s28, v142, v162
	v_exp_f32_e32 v109, v48
	ds_read2_b64 v[48:51], v110 offset1:2
	v_sub_f32_e32 v52, v56, v96
	v_exp_f32_e32 v111, v52
	v_cvt_pk_bf16_f32 v52, v80, v81
	v_cvt_pk_bf16_f32 v53, v82, v83
	v_cvt_pk_bf16_f32 v54, v84, v85
	v_cvt_pk_bf16_f32 v55, v86, v87
	v_add_u32_e32 v80, 0x2000, v110
	ds_read2_b64 v[64:67], v80 offset0:32 offset1:34
	s_waitcnt lgkmcnt(1)
	v_mfma_f32_32x32x16_bf16 v[16:31], v[48:51], v[52:55], v[16:31]
	v_add_f32_e32 v48, v107, v106
	v_add_f32_e32 v48, v108, v48
	v_add_f32_e32 v48, v109, v48
	v_add_f32_e32 v56, v111, v48
	v_sub_f32_e32 v48, v57, v96
	v_exp_f32_e32 v81, v48
	ds_read2_b64 v[48:51], v110 offset0:4 offset1:6
	s_waitcnt lgkmcnt(1)
	v_mfma_f32_32x32x16_bf16 v[0:15], v[64:67], v[52:55], v[0:15]
	v_sub_f32_e32 v52, v58, v96
	v_exp_f32_e32 v82, v52
	v_cvt_pk_bf16_f32 v52, v88, v89
	v_cvt_pk_bf16_f32 v53, v90, v91
	v_cvt_pk_bf16_f32 v54, v92, v93
	v_cvt_pk_bf16_f32 v55, v94, v95
	ds_read2_b64 v[64:67], v80 offset0:36 offset1:38
	v_sub_f32_e32 v32, v32, v96
	s_waitcnt lgkmcnt(1)
	v_mfma_f32_32x32x16_bf16 v[16:31], v[48:51], v[52:55], v[16:31]
	v_add_f32_e32 v48, v81, v56
	v_add_f32_e32 v83, v82, v48
	v_sub_f32_e32 v48, v59, v96
	v_exp_f32_e32 v84, v48
	v_sub_f32_e32 v48, v60, v96
	v_exp_f32_e32 v60, v48
	ds_read2_b64 v[48:51], v110 offset0:8 offset1:10
	s_waitcnt lgkmcnt(1)
	v_mfma_f32_32x32x16_bf16 v[0:15], v[64:67], v[52:55], v[0:15]
	v_sub_f32_e32 v52, v61, v96
	v_exp_f32_e32 v61, v52
	v_cvt_pk_bf16_f32 v52, v98, v97
	v_cvt_pk_bf16_f32 v53, v99, v100
	v_cvt_pk_bf16_f32 v54, v68, v69
	v_cvt_pk_bf16_f32 v55, v70, v71
	ds_read2_b64 v[56:59], v80 offset0:40 offset1:42
	v_exp_f32_e32 v65, v32
	s_waitcnt lgkmcnt(1)
	v_mfma_f32_32x32x16_bf16 v[16:31], v[48:51], v[52:55], v[16:31]
	v_sub_f32_e32 v48, v62, v96
	v_exp_f32_e32 v62, v48
	v_add_f32_e32 v48, v84, v83
	v_add_f32_e32 v48, v60, v48
	v_add_f32_e32 v48, v61, v48
	v_add_f32_e32 v64, v62, v48
	ds_read2_b64 v[48:51], v110 offset0:12 offset1:14
	s_waitcnt lgkmcnt(1)
	v_mfma_f32_32x32x16_bf16 v[0:15], v[56:59], v[52:55], v[0:15]
	ds_read2_b64 v[56:59], v80 offset0:44 offset1:46
	v_sub_f32_e32 v52, v63, v96
	v_exp_f32_e32 v63, v52
	v_cvt_pk_bf16_f32 v52, v72, v73
	v_cvt_pk_bf16_f32 v53, v74, v75
	v_cvt_pk_bf16_f32 v54, v76, v77
	v_cvt_pk_bf16_f32 v55, v78, v79
	v_sub_f32_e32 v32, v33, v96
	v_exp_f32_e32 v66, v32
	s_waitcnt lgkmcnt(1)
	v_mfma_f32_32x32x16_bf16 v[16:31], v[48:51], v[52:55], v[16:31]
	ds_read2_b64 v[48:51], v110 offset0:16 offset1:18
	v_sub_f32_e32 v32, v34, v96
	v_cvt_pk_bf16_f32 v33, v103, v104
	v_cvt_pk_bf16_f32 v34, v105, v107
	v_sub_f32_e32 v36, v36, v96
	v_sub_f32_e32 v40, v40, v96
	v_sub_f32_e32 v46, v46, v96
	s_waitcnt lgkmcnt(1)
	v_mfma_f32_32x32x16_bf16 v[0:15], v[56:59], v[52:55], v[0:15]
	ds_read2_b64 v[52:55], v80 offset0:48 offset1:50
	v_exp_f32_e32 v56, v32
	v_sub_f32_e32 v57, v35, v96
	v_cvt_pk_bf16_f32 v32, v101, v102
	v_cvt_pk_bf16_f32 v35, v108, v109
	v_exp_f32_e32 v58, v36
	v_sub_f32_e32 v36, v37, v96
	s_waitcnt lgkmcnt(1)
	v_mfma_f32_32x32x16_bf16 v[16:31], v[48:51], v[32:35], v[16:31]
	ds_read2_b64 v[48:51], v110 offset0:20 offset1:22
	v_exp_f32_e32 v59, v36
	v_sub_f32_e32 v36, v38, v96
	v_exp_f32_e32 v57, v57
	v_exp_f32_e32 v46, v46
	v_add_f32_e32 v64, v63, v64
	s_lshl_b32 s10, s30, 7
	s_waitcnt lgkmcnt(1)
	v_mfma_f32_32x32x16_bf16 v[0:15], v[52:55], v[32:35], v[0:15]
	v_exp_f32_e32 v52, v36
	v_sub_f32_e32 v53, v39, v96
	ds_read2_b64 v[36:39], v80 offset0:52 offset1:54
	v_cvt_pk_bf16_f32 v32, v111, v81
	v_cvt_pk_bf16_f32 v33, v82, v84
	v_cvt_pk_bf16_f32 v34, v60, v61
	v_cvt_pk_bf16_f32 v35, v62, v63
	v_exp_f32_e32 v53, v53
	v_exp_f32_e32 v54, v40
	s_waitcnt lgkmcnt(1)
	v_mfma_f32_32x32x16_bf16 v[16:31], v[48:51], v[32:35], v[16:31]
	ds_read2_b64 v[48:51], v110 offset0:24 offset1:26
	v_sub_f32_e32 v40, v41, v96
	v_exp_f32_e32 v55, v40
	v_sub_f32_e32 v40, v42, v96
	v_exp_f32_e32 v60, v40
	v_sub_f32_e32 v40, v43, v96
	s_add_i32 s29, s29, s90
	s_waitcnt lgkmcnt(1)
	v_mfma_f32_32x32x16_bf16 v[0:15], v[36:39], v[32:35], v[0:15]
	ds_read2_b64 v[36:39], v80 offset0:56 offset1:58
	v_cvt_pk_bf16_f32 v32, v65, v66
	v_cvt_pk_bf16_f32 v33, v56, v57
	v_cvt_pk_bf16_f32 v34, v58, v59
	v_cvt_pk_bf16_f32 v35, v52, v53
	s_add_i32 s2, s37, s33
	s_cmpk_gt_i32 s29, 0xff
	s_waitcnt lgkmcnt(1)
	v_mfma_f32_32x32x16_bf16 v[16:31], v[48:51], v[32:35], v[16:31]
	v_exp_f32_e32 v48, v40
	v_sub_f32_e32 v40, v44, v96
	v_exp_f32_e32 v44, v40
	v_sub_f32_e32 v40, v45, v96
	v_exp_f32_e32 v45, v40
	ds_read2_b64 v[40:43], v110 offset0:28 offset1:30
	s_waitcnt lgkmcnt(1)
	v_mfma_f32_32x32x16_bf16 v[0:15], v[36:39], v[32:35], v[0:15]
	v_sub_f32_e32 v32, v47, v96
	v_exp_f32_e32 v47, v32
	v_cvt_pk_bf16_f32 v32, v54, v55
	v_cvt_pk_bf16_f32 v33, v60, v48
	v_cvt_pk_bf16_f32 v34, v44, v45
	v_cvt_pk_bf16_f32 v35, v46, v47
	ds_read2_b64 v[36:39], v80 offset0:60 offset1:62
	s_waitcnt lgkmcnt(0)
	v_mfma_f32_32x32x16_bf16 v[16:31], v[40:43], v[32:35], v[16:31]
	v_add_f32_e32 v40, v65, v64
	v_add_f32_e32 v40, v66, v40
	v_add_f32_e32 v40, v56, v40
	v_add_f32_e32 v40, v57, v40
	v_add_f32_e32 v40, v58, v40
	v_add_f32_e32 v40, v59, v40
	v_add_f32_e32 v40, v52, v40
	v_add_f32_e32 v40, v53, v40
	v_add_f32_e32 v40, v54, v40
	v_add_f32_e32 v40, v55, v40
	v_add_f32_e32 v40, v60, v40
	v_add_f32_e32 v40, v48, v40
	v_add_f32_e32 v40, v44, v40
	v_add_f32_e32 v40, v45, v40
	v_add_f32_e32 v40, v46, v40
	v_add_f32_e32 v40, v47, v40
	v_add_f32_e32 v40, v149, v40
	ds_bpermute_b32 v41, v147, v40
	v_mfma_f32_32x32x16_bf16 v[0:15], v[36:39], v[32:35], v[0:15]
	s_barrier
	s_cselect_b32 s101, 1, 0
	s_cmp_lg_u32 s100, 0
	s_cbranch_scc1 .Latt1_nofin
	s_barrier
.Latt1_nofin:
	s_cmp_lg_u32 s101, 0
	s_waitcnt lgkmcnt(0)
	v_add_f32_e32 v32, v40, v41
	v_div_scale_f32 v33, s[4:5], v32, v32, 1.0
	v_rcp_f32_e32 v34, v33
	s_nop 0
	v_fma_f32 v35, -v33, v34, 1.0
	v_fmac_f32_e32 v34, v35, v34
	v_div_scale_f32 v35, vcc, 1.0, v32, 1.0
	v_mul_f32_e32 v36, v35, v34
	v_fma_f32 v37, -v33, v36, v35
	v_fmac_f32_e32 v36, v37, v34
	v_fma_f32 v33, -v33, v36, v35
	v_div_fmas_f32 v33, v33, v34, v36
	v_lshlrev_b64 v[34:35], 11, v[144:145]
	v_div_fixup_f32 v32, v33, v32, 1.0
	v_lshl_add_u64 v[34:35], s[8:9], 0, v[34:35]
	v_lshl_add_u64 v[34:35], v[34:35], 0, s[10:11]
	v_pk_mul_f32 v[16:17], v[16:17], v[32:33] op_sel_hi:[1,0]
	v_pk_mul_f32 v[18:19], v[18:19], v[32:33] op_sel_hi:[1,0]
	v_pk_mul_f32 v[0:1], v[0:1], v[32:33] op_sel_hi:[1,0]
	v_pk_mul_f32 v[2:3], v[2:3], v[32:33] op_sel_hi:[1,0]
	v_lshl_add_u64 v[34:35], v[34:35], 0, v[142:143]
	v_cvt_pk_bf16_f32 v16, v16, v17
	v_cvt_pk_bf16_f32 v17, v18, v19
	v_cvt_pk_bf16_f32 v0, v0, v1
	v_cvt_pk_bf16_f32 v1, v2, v3
	global_store_dwordx2 v[34:35], v[16:17], off
	v_pk_mul_f32 v[16:17], v[20:21], v[32:33] op_sel_hi:[1,0]
	v_pk_mul_f32 v[18:19], v[22:23], v[32:33] op_sel_hi:[1,0]
	global_store_dwordx2 v[34:35], v[0:1], off offset:64
	v_pk_mul_f32 v[0:1], v[4:5], v[32:33] op_sel_hi:[1,0]
	v_pk_mul_f32 v[2:3], v[6:7], v[32:33] op_sel_hi:[1,0]
	v_cvt_pk_bf16_f32 v16, v16, v17
	v_cvt_pk_bf16_f32 v17, v18, v19
	v_cvt_pk_bf16_f32 v0, v0, v1
	v_cvt_pk_bf16_f32 v1, v2, v3
	global_store_dwordx2 v[34:35], v[16:17], off offset:16
	v_pk_mul_f32 v[16:17], v[24:25], v[32:33] op_sel_hi:[1,0]
	v_pk_mul_f32 v[18:19], v[26:27], v[32:33] op_sel_hi:[1,0]
	global_store_dwordx2 v[34:35], v[0:1], off offset:80
	v_pk_mul_f32 v[0:1], v[8:9], v[32:33] op_sel_hi:[1,0]
	v_pk_mul_f32 v[2:3], v[10:11], v[32:33] op_sel_hi:[1,0]
	v_cvt_pk_bf16_f32 v16, v16, v17
	v_cvt_pk_bf16_f32 v17, v18, v19
	v_cvt_pk_bf16_f32 v0, v0, v1
	v_cvt_pk_bf16_f32 v1, v2, v3
	global_store_dwordx2 v[34:35], v[16:17], off offset:32
	v_pk_mul_f32 v[16:17], v[28:29], v[32:33] op_sel_hi:[1,0]
	v_pk_mul_f32 v[18:19], v[30:31], v[32:33] op_sel_hi:[1,0]
	global_store_dwordx2 v[34:35], v[0:1], off offset:96
	v_pk_mul_f32 v[0:1], v[12:13], v[32:33] op_sel_hi:[1,0]
	v_pk_mul_f32 v[2:3], v[14:15], v[32:33] op_sel_hi:[1,0]
	v_cvt_pk_bf16_f32 v16, v16, v17
	v_cvt_pk_bf16_f32 v17, v18, v19
	v_cvt_pk_bf16_f32 v0, v0, v1
	v_cvt_pk_bf16_f32 v1, v2, v3
	global_store_dwordx2 v[34:35], v[16:17], off offset:48
	global_store_dwordx2 v[34:35], v[0:1], off offset:112
	s_cbranch_scc1 .LBB0_2135
.LBB0_2126:
	s_lshl_b32 s4, s29, 1
	s_and_b32 s5, s4, 14
	s_ashr_i32 s4, s29, 7
	s_add_i32 s36, s5, s4
	s_lshl_b32 s5, s36, 10
	s_lshl_b32 s10, s29, 5
	s_mov_b32 s37, s2
	s_and_b32 s2, s2, 14
	s_and_b32 s30, s36, 3
	s_and_b32 s5, s5, 0xfffff000
	s_and_b32 s31, s10, 0xf00
	s_mul_i32 s18, s36, 0xcc000
	s_waitcnt vmcnt(0)
	v_mov_b32_e32 v8, v164
	s_mul_hi_i32 s10, s36, 0xcc000
	s_add_u32 s18, s0, s18
	v_ashrrev_i32_e32 v17, 1, v8
	s_addc_u32 s19, s1, s10
	v_bfi_b32 v0, s21, v17, v8
	s_or_b32 s5, s5, s31
	v_add_u32_e32 v144, s5, v0
	v_bfe_u32 v9, v8, 5, 1
	v_mad_i64_i32 v[0:1], s[34:35], v144, s24, v[140:141]
	s_mul_i32 s10, s30, 0xc0
	v_lshl_add_u64 v[30:31], v[0:1], 0, s[10:11]
	v_lshlrev_b32_e32 v142, 4, v9
	v_lshl_add_u64 v[10:11], v[30:31], 0, v[142:143]
	global_load_dwordx4 v[0:3], v[10:11], off
	global_load_dwordx4 v[4:7], v[10:11], off offset:32
	global_load_dwordx4 v[12:15], v[10:11], off offset:64
	global_load_dwordx4 v[18:21], v[10:11], off offset:96
	global_load_dwordx4 v[22:25], v[30:31], off offset:144
	global_load_dwordx4 v[26:29], v[30:31], off offset:128
	v_and_b32_e32 v10, 31, v8
	v_and_b32_e32 v11, 0xffffffe0, v17
	v_cmp_eq_u32_e32 vcc, 0, v9
	s_mul_i32 s10, s36, 0x88000
	s_mul_hi_i32 s5, s36, 0x88000
	s_add_u32 s34, s13, s10
	s_addc_u32 s35, s20, s5
	v_lshlrev_b32_e32 v16, 3, v9
	v_lshlrev_b32_e32 v169, 1, v16
	v_ashrrev_i32_e32 v145, 31, v144
	v_mov_b32_e32 v172, 0xf149f2ca
	s_waitcnt vmcnt(5)
	v_lshlrev_b32_e32 v32, 16, v0
	v_and_b32_e32 v33, 0xffff0000, v0
	v_lshlrev_b32_e32 v0, 16, v1
	v_and_b32_e32 v1, 0xffff0000, v1
	v_pk_mul_f32 v[0:1], v[0:1], s[12:13] op_sel_hi:[1,0]
	v_lshlrev_b32_e32 v34, 16, v2
	v_cvt_pk_bf16_f32 v109, v0, v1
	s_waitcnt vmcnt(2)
	v_lshlrev_b32_e32 v0, 16, v20
	v_and_b32_e32 v1, 0xffff0000, v20
	v_pk_mul_f32 v[0:1], v[0:1], s[12:13] op_sel_hi:[1,0]
	v_and_b32_e32 v35, 0xffff0000, v2
	v_cvt_pk_bf16_f32 v98, v0, v1
	v_lshlrev_b32_e32 v0, 16, v21
	v_and_b32_e32 v1, 0xffff0000, v21
	v_pk_mul_f32 v[0:1], v[0:1], s[12:13] op_sel_hi:[1,0]
	v_lshlrev_b32_e32 v2, 16, v3
	v_cvt_pk_bf16_f32 v99, v0, v1
	v_add_u32_e32 v0, s31, v17
	v_and_b32_e32 v3, 0xffff0000, v3
	v_lshlrev_b32_e32 v36, 16, v4
	v_and_b32_e32 v37, 0xffff0000, v4
	v_lshlrev_b32_e32 v4, 16, v5
	v_and_b32_e32 v5, 0xffff0000, v5
	v_lshlrev_b32_e32 v38, 16, v6
	v_and_b32_e32 v39, 0xffff0000, v6
	v_lshlrev_b32_e32 v6, 16, v7
	v_and_b32_e32 v7, 0xffff0000, v7
	v_ashrrev_i32_e32 v0, 6, v0
	v_pk_mul_f32 v[2:3], v[2:3], s[12:13] op_sel_hi:[1,0]
	v_pk_mul_f32 v[4:5], v[4:5], s[12:13] op_sel_hi:[1,0]
	v_pk_mul_f32 v[6:7], v[6:7], s[12:13] op_sel_hi:[1,0]
	v_cvt_f32_i32_e32 v17, v0
	v_bitop3_b32 v0, v11, 63, v10 bitop3:0xc8
	v_cvt_pk_bf16_f32 v111, v2, v3
	v_cvt_pk_bf16_f32 v105, v4, v5
	v_cvt_pk_bf16_f32 v107, v6, v7
	v_cvt_f32_ubyte0_e32 v11, v0
	global_load_dwordx4 v[0:3], v[30:31], off offset:176
	global_load_dwordx4 v[4:7], v[30:31], off offset:160
	v_lshlrev_b32_e32 v40, 16, v12
	v_and_b32_e32 v41, 0xffff0000, v12
	v_lshlrev_b32_e32 v12, 16, v13
	v_and_b32_e32 v13, 0xffff0000, v13
	v_lshlrev_b32_e32 v42, 16, v14
	v_and_b32_e32 v43, 0xffff0000, v14
	v_lshlrev_b32_e32 v14, 16, v15
	v_and_b32_e32 v15, 0xffff0000, v15
	v_pk_mul_f32 v[12:13], v[12:13], s[12:13] op_sel_hi:[1,0]
	v_pk_mul_f32 v[14:15], v[14:15], s[12:13] op_sel_hi:[1,0]
	v_cvt_pk_bf16_f32 v101, v12, v13
	v_mul_f32_e32 v13, 0.15915494, v17
	v_cvt_pk_bf16_f32 v103, v14, v15
	v_cos_f32_e32 v12, v13
	v_sin_f32_e32 v14, v13
	v_mul_f32_e32 v13, 0x3ea1e89b, v17
	v_mul_f32_e32 v15, 0.15915494, v13
	v_cos_f32_e32 v13, v15
	v_sin_f32_e32 v15, v15
	v_lshlrev_b32_e32 v44, 16, v18
	v_and_b32_e32 v45, 0xffff0000, v18
	v_lshlrev_b32_e32 v18, 16, v19
	v_and_b32_e32 v19, 0xffff0000, v19
	v_pk_mul_f32 v[18:19], v[18:19], s[12:13] op_sel_hi:[1,0]
	s_waitcnt vmcnt(3)
	v_lshlrev_b32_e32 v20, 16, v22
	v_and_b32_e32 v21, 0xffff0000, v22
	v_cvt_pk_bf16_f32 v97, v18, v19
	s_waitcnt vmcnt(2)
	v_lshlrev_b32_e32 v18, 16, v26
	v_and_b32_e32 v19, 0xffff0000, v26
	v_pk_mul_f32 v[30:31], v[14:15], v[20:21]
	v_lshlrev_b32_e32 v22, 16, v23
	v_pk_fma_f32 v[30:31], v[12:13], v[18:19], v[30:31] neg_lo:[0,0,1] neg_hi:[0,0,1]
	v_pk_mul_f32 v[12:13], v[12:13], v[20:21]
	v_and_b32_e32 v23, 0xffff0000, v23
	v_pk_fma_f32 v[12:13], v[14:15], v[18:19], v[12:13]
	v_mul_f32_e32 v14, 0x3dcccccd, v17
	v_mul_f32_e32 v15, 0.15915494, v14
	v_cos_f32_e32 v14, v15
	v_sin_f32_e32 v18, v15
	v_mul_f32_e32 v15, 0x3d0186e3, v17
	v_mul_f32_e32 v19, 0.15915494, v15
	v_cos_f32_e32 v15, v19
	v_sin_f32_e32 v19, v19
	v_lshlrev_b32_e32 v20, 16, v27
	v_and_b32_e32 v21, 0xffff0000, v27
	v_cndmask_b32_e32 v13, v13, v31, vcc
	v_pk_mul_f32 v[26:27], v[18:19], v[22:23]
	v_cndmask_b32_e32 v12, v12, v30, vcc
	v_pk_fma_f32 v[26:27], v[14:15], v[20:21], v[26:27] neg_lo:[0,0,1] neg_hi:[0,0,1]
	v_pk_mul_f32 v[14:15], v[14:15], v[22:23]
	v_lshlrev_b32_e32 v22, 16, v28
	v_pk_fma_f32 v[14:15], v[18:19], v[20:21], v[14:15]
	v_mul_f32_e32 v18, 0x3c23d70b, v17
	v_mul_f32_e32 v19, 0.15915494, v18
	v_cos_f32_e32 v18, v19
	v_sin_f32_e32 v20, v19
	v_mul_f32_e32 v19, 0x3b4f3e39, v17
	v_mul_f32_e32 v21, 0.15915494, v19
	v_cos_f32_e32 v19, v21
	v_sin_f32_e32 v21, v21
	v_cndmask_b32_e32 v15, v15, v27, vcc
	v_cndmask_b32_e32 v14, v14, v26, vcc
	v_lshlrev_b32_e32 v26, 16, v24
	v_and_b32_e32 v27, 0xffff0000, v24
	v_and_b32_e32 v23, 0xffff0000, v28
	v_pk_mul_f32 v[30:31], v[20:21], v[26:27]
	v_pk_mul_f32 v[12:13], v[12:13], s[12:13] op_sel_hi:[1,0]
	v_pk_fma_f32 v[30:31], v[18:19], v[22:23], v[30:31] neg_lo:[0,0,1] neg_hi:[0,0,1]
	v_pk_mul_f32 v[18:19], v[18:19], v[26:27]
	v_pk_mul_f32 v[14:15], v[14:15], s[12:13] op_sel_hi:[1,0]
	v_pk_fma_f32 v[18:19], v[20:21], v[22:23], v[18:19]
	v_mul_f32_e32 v20, 0x3a831270, v17
	v_mul_f32_e32 v17, 0x39a5cb61, v17
	v_mul_f32_e32 v21, 0.15915494, v20
	v_mul_f32_e32 v17, 0.15915494, v17
	v_sin_f32_e32 v22, v21
	v_sin_f32_e32 v23, v17
	v_cos_f32_e32 v20, v21
	v_cos_f32_e32 v21, v17
	v_lshlrev_b32_e32 v24, 16, v25
	v_and_b32_e32 v25, 0xffff0000, v25
	v_cvt_pk_bf16_f32 v112, v12, v13
	v_mul_f32_e32 v13, 0.15915494, v11
	v_lshlrev_b32_e32 v26, 16, v29
	v_and_b32_e32 v27, 0xffff0000, v29
	v_pk_mul_f32 v[28:29], v[22:23], v[24:25]
	v_cvt_pk_bf16_f32 v113, v14, v15
	v_cos_f32_e32 v12, v13
	v_sin_f32_e32 v14, v13
	v_mul_f32_e32 v13, 0x3ea1e89b, v11
	v_pk_fma_f32 v[28:29], v[20:21], v[26:27], v[28:29] neg_lo:[0,0,1] neg_hi:[0,0,1]
	v_pk_mul_f32 v[20:21], v[20:21], v[24:25]
	v_mul_f32_e32 v15, 0.15915494, v13
	v_pk_fma_f32 v[20:21], v[22:23], v[26:27], v[20:21]
	v_cos_f32_e32 v13, v15
	v_sin_f32_e32 v15, v15
	v_cndmask_b32_e32 v21, v21, v29, vcc
	v_cndmask_b32_e32 v20, v20, v28, vcc
	v_cndmask_b32_e32 v19, v19, v31, vcc
	v_cndmask_b32_e32 v18, v18, v30, vcc
	v_pk_mul_f32 v[20:21], v[20:21], s[12:13] op_sel_hi:[1,0]
	v_pk_mul_f32 v[18:19], v[18:19], s[12:13] op_sel_hi:[1,0]
	v_cvt_pk_bf16_f32 v115, v20, v21
	s_waitcnt vmcnt(1)
	v_lshlrev_b32_e32 v20, 16, v0
	v_and_b32_e32 v21, 0xffff0000, v0
	v_cvt_pk_bf16_f32 v114, v18, v19
	s_waitcnt vmcnt(0)
	v_lshlrev_b32_e32 v18, 16, v4
	v_and_b32_e32 v19, 0xffff0000, v4
	v_pk_mul_f32 v[22:23], v[14:15], v[20:21]
	v_mul_f32_e32 v0, 0x3dcccccd, v11
	v_pk_fma_f32 v[22:23], v[12:13], v[18:19], v[22:23] neg_lo:[0,0,1] neg_hi:[0,0,1]
	v_pk_mul_f32 v[12:13], v[12:13], v[20:21]
	v_pk_mul_f32 v[34:35], v[34:35], s[12:13] op_sel_hi:[1,0]
	v_pk_fma_f32 v[12:13], v[14:15], v[18:19], v[12:13]
	v_mul_f32_e32 v0, 0.15915494, v0
	v_cndmask_b32_e32 v13, v13, v23, vcc
	v_cndmask_b32_e32 v12, v12, v22, vcc
	v_cvt_pk_bf16_f32 v110, v34, v35
	v_pk_mul_f32 v[34:35], v[12:13], s[12:13] op_sel_hi:[1,0]
	v_cos_f32_e32 v12, v0
	v_sin_f32_e32 v14, v0
	v_mul_f32_e32 v0, 0x3d0186e3, v11
	v_mul_f32_e32 v0, 0.15915494, v0
	v_cos_f32_e32 v13, v0
	v_sin_f32_e32 v15, v0
	v_lshlrev_b32_e32 v0, 16, v1
	v_and_b32_e32 v1, 0xffff0000, v1
	v_lshlrev_b32_e32 v4, 16, v5
	v_and_b32_e32 v5, 0xffff0000, v5
	v_pk_mul_f32 v[18:19], v[14:15], v[0:1]
	v_pk_mul_f32 v[0:1], v[12:13], v[0:1]
	v_pk_fma_f32 v[18:19], v[12:13], v[4:5], v[18:19] neg_lo:[0,0,1] neg_hi:[0,0,1]
	v_pk_fma_f32 v[0:1], v[14:15], v[4:5], v[0:1]
	v_mul_f32_e32 v4, 0x3c23d70b, v11
	v_pk_mul_f32 v[36:37], v[36:37], s[12:13] op_sel_hi:[1,0]
	v_mul_f32_e32 v5, 0.15915494, v4
	v_cvt_pk_bf16_f32 v104, v36, v37
	v_cos_f32_e32 v4, v5
	v_sin_f32_e32 v36, v5
	v_mul_f32_e32 v5, 0x3b4f3e39, v11
	v_mul_f32_e32 v37, 0.15915494, v5
	v_cos_f32_e32 v5, v37
	v_sin_f32_e32 v37, v37
	v_lshlrev_b32_e32 v22, 3, v8
	v_lshlrev_b32_e32 v52, 16, v2
	v_and_b32_e32 v53, 0xffff0000, v2
	v_pk_mul_f32 v[38:39], v[38:39], s[12:13] op_sel_hi:[1,0]
	v_pk_mul_f32 v[40:41], v[40:41], s[12:13] op_sel_hi:[1,0]
	v_ashrrev_i32_e32 v23, 31, v22
	v_add_u32_e32 v14, 0x1000, v22
	v_lshlrev_b32_e32 v50, 16, v6
	v_and_b32_e32 v51, 0xffff0000, v6
	v_pk_mul_f32 v[54:55], v[36:37], v[52:53]
	v_mul_f32_e32 v2, 0x3a831270, v11
	v_pk_mul_f32 v[42:43], v[42:43], s[12:13] op_sel_hi:[1,0]
	v_cvt_pk_bf16_f32 v106, v38, v39
	v_cvt_pk_bf16_f32 v100, v40, v41
	v_and_b32_e32 v38, 0x78, v22
	v_lshlrev_b64 v[40:41], 1, v[22:23]
	v_ashrrev_i32_e32 v15, 31, v14
	v_add_u32_e32 v22, 0x2000, v22
	v_pk_fma_f32 v[54:55], v[4:5], v[50:51], v[54:55] neg_lo:[0,0,1] neg_hi:[0,0,1]
	v_pk_mul_f32 v[4:5], v[4:5], v[52:53]
	v_mul_f32_e32 v2, 0.15915494, v2
	v_pk_mul_f32 v[44:45], v[44:45], s[12:13] op_sel_hi:[1,0]
	v_cvt_pk_bf16_f32 v102, v42, v43
	v_lshlrev_b64 v[42:43], 1, v[14:15]
	v_ashrrev_i32_e32 v23, 31, v22
	v_pk_fma_f32 v[4:5], v[36:37], v[50:51], v[4:5]
	v_cos_f32_e32 v36, v2
	v_sin_f32_e32 v50, v2
	v_mul_f32_e32 v2, 0x39a5cb61, v11
	v_cvt_pk_bf16_f32 v96, v44, v45
	v_cndmask_b32_e32 v1, v1, v19, vcc
	v_cndmask_b32_e32 v0, v0, v18, vcc
	v_lshl_add_u64 v[12:13], s[18:19], 0, v[40:41]
	v_lshl_add_u64 v[18:19], s[18:19], 0, v[42:43]
	v_lshlrev_b64 v[44:45], 1, v[22:23]
	v_mul_f32_e32 v2, 0.15915494, v2
	v_ashrrev_i32_e32 v39, 4, v8
	global_load_dwordx4 v[12:15], v[12:13], off
	s_nop 0
	global_load_dwordx4 v[18:21], v[18:19], off
	v_lshl_add_u64 v[22:23], s[18:19], 0, v[44:45]
	v_mov_b64_e32 v[30:31], s[34:35]
	v_cos_f32_e32 v37, v2
	v_sin_f32_e32 v51, v2
	v_add_u32_e32 v17, 0x200, v8
	global_load_dwordx4 v[22:25], v[22:23], off
	v_mad_i64_i32 v[26:27], s[34:35], v39, s26, v[30:31]
	v_lshlrev_b32_e32 v142, 1, v38
	v_lshl_add_u64 v[46:47], v[26:27], 0, v[142:143]
	v_ashrrev_i32_e32 v56, 4, v17
	global_load_dwordx4 v[26:29], v[46:47], off
	v_mad_i64_i32 v[30:31], s[34:35], v56, s26, v[30:31]
	v_lshlrev_b32_e32 v2, 16, v3
	v_and_b32_e32 v3, 0xffff0000, v3
	v_pk_mul_f32 v[32:33], v[32:33], s[12:13] op_sel_hi:[1,0]
	v_lshl_add_u64 v[48:49], v[30:31], 0, v[142:143]
	v_lshlrev_b32_e32 v6, 16, v7
	v_and_b32_e32 v7, 0xffff0000, v7
	v_pk_mul_f32 v[52:53], v[50:51], v[2:3]
	v_pk_mul_f32 v[2:3], v[36:37], v[2:3]
	v_cvt_pk_bf16_f32 v108, v32, v33
	global_load_dwordx4 v[30:33], v[48:49], off
	v_pk_fma_f32 v[52:53], v[36:37], v[6:7], v[52:53] neg_lo:[0,0,1] neg_hi:[0,0,1]
	v_pk_fma_f32 v[2:3], v[50:51], v[6:7], v[2:3]
	v_pk_mul_f32 v[0:1], v[0:1], s[12:13] op_sel_hi:[1,0]
	v_cndmask_b32_e32 v3, v3, v53, vcc
	v_cndmask_b32_e32 v2, v2, v52, vcc
	s_add_u32 s18, s18, 0x6000
	v_cndmask_b32_e32 v5, v5, v55, vcc
	v_cndmask_b32_e32 v4, v4, v54, vcc
	v_pk_mul_f32 v[2:3], v[2:3], s[12:13] op_sel_hi:[1,0]
	v_cvt_pk_bf16_f32 v117, v0, v1
	v_mul_hi_i32 v0, v8, s25
	s_addc_u32 s19, s19, 0
	v_pk_mul_f32 v[4:5], v[4:5], s[12:13] op_sel_hi:[1,0]
	v_cvt_pk_bf16_f32 v119, v2, v3
	v_lshrrev_b32_e32 v1, 31, v0
	v_ashrrev_i32_e32 v0, 1, v0
	v_lshl_add_u64 v[2:3], s[18:19], 0, v[42:43]
	v_cvt_pk_bf16_f32 v118, v4, v5
	v_add3_u32 v6, v0, v1, v8
	v_lshl_add_u64 v[0:1], s[18:19], 0, v[40:41]
	v_lshl_add_u64 v[4:5], s[18:19], 0, v[44:45]
	global_load_dwordx4 v[120:123], v[2:3], off
	global_load_dwordx4 v[128:131], v[4:5], off
	global_load_dwordx4 v[132:135], v[46:47], off offset:256
	global_load_dwordx4 v[124:127], v[0:1], off
	global_load_dwordx4 v[136:139], v[48:49], off offset:256
	v_mul_hi_i32 v7, v17, s25
	v_add_u32_e32 v1, 0x400, v8
	v_lshrrev_b32_e32 v11, 31, v7
	v_ashrrev_i32_e32 v0, 1, v7
	v_mul_hi_i32 v2, v1, s25
	v_add3_u32 v0, v0, v11, v17
	v_lshrrev_b32_e32 v3, 31, v2
	v_ashrrev_i32_e32 v2, 1, v2
	v_lshlrev_b32_e32 v167, 3, v0
	v_add3_u32 v1, v2, v3, v1
	v_lshl_add_u32 v2, v6, 4, 0
	v_lshl_add_u32 v0, v0, 4, 0
	v_mad_u64_u32 v[146:147], s[18:19], v39, s27, v[38:39]
	v_mad_u64_u32 v[148:149], s[18:19], v56, s27, v[38:39]
	s_add_i32 s2, s4, s2
	s_mul_i32 s4, s2, 0x88000
	v_cmp_lt_i32_e32 vcc, v160, v161
	s_mul_hi_i32 s5, s2, 0x88000
	s_add_u32 s4, s4, 0xc1e6200
	s_addc_u32 s5, s5, 0
	v_lshlrev_b32_e32 v168, 3, v1
	v_lshlrev_b32_e32 v17, 2, v9
	v_lshlrev_b32_e32 v163, 3, v6
	v_mov_b32_e32 v3, v143
	v_mov_b32_e32 v4, v143
	v_mov_b32_e32 v5, v143
	v_mov_b32_e32 v6, v143
	v_mov_b32_e32 v7, v143
	v_mov_b32_e32 v9, v143
	v_mov_b32_e32 v11, v143
	s_waitcnt vmcnt(9)
	ds_write_b128 v2, v[12:15]
	s_waitcnt vmcnt(8)
	ds_write_b128 v0, v[18:21]
	v_lshl_add_u32 v0, v1, 4, 0
	v_lshlrev_b32_e32 v2, 4, v8
	v_mul_u32_u24_e32 v18, 0x68, v10
	v_mul_u32_u24_e32 v19, 0x84, v10
	v_and_b32_e32 v2, 0xf0, v2
	s_waitcnt vmcnt(7)
	ds_write_b128 v0, v[22:25]
	v_lshl_add_u32 v0, v146, 1, 0
	v_add_u32_e32 v0, 0x6800, v0
	v_mov_b32_e32 v14, v143
	v_mov_b32_e32 v15, v143
	v_mov_b32_e32 v8, v143
	s_waitcnt vmcnt(6)
	ds_write2_b64 v0, v[26:27], v[28:29] offset1:1
	v_lshl_add_u32 v0, v148, 1, 0
	v_add_u32_e32 v0, 0x6800, v0
	v_mov_b32_e32 v10, v143
	v_mov_b32_e32 v12, v143
	v_mov_b32_e32 v13, v143
	v_lshlrev_b32_e32 v170, 1, v18
	v_lshlrev_b32_e32 v142, 1, v17
	v_lshlrev_b32_e32 v162, 1, v19
	v_cvt_pk_bf16_f32 v116, v34, v35
	v_mov_b32_e32 v149, 0
	s_waitcnt vmcnt(5)
	ds_write2_b64 v0, v[30:31], v[32:33] offset1:1
	v_cndmask_b32_e32 v0, v165, v160, vcc
	v_lshlrev_b32_e32 v147, 2, v0
	v_mov_b64_e32 v[0:1], s[4:5]
	v_mad_i64_i32 v[150:151], s[4:5], v56, s26, v[0:1]
	v_mad_i64_i32 v[152:153], s[4:5], v39, s26, v[0:1]
	s_mul_hi_i32 s5, s2, 0xcc000
	s_mul_i32 s2, s2, 0xcc000
	s_add_u32 s4, s2, 0xb532000
	v_or_b32_e32 v150, v150, v2
	v_or_b32_e32 v152, v152, v2
	s_addc_u32 s5, s5, 0
	v_mov_b32_e32 v0, v143
	v_mov_b32_e32 v1, v143
	v_mov_b32_e32 v2, v143
	v_mov_b64_e32 v[30:31], v[14:15]
	v_lshl_add_u64 v[154:155], s[4:5], 0, v[40:41]
	v_lshl_add_u64 v[156:157], s[4:5], 0, v[42:43]
	v_lshl_add_u64 v[158:159], s[4:5], 0, v[44:45]
	v_mov_b64_e32 v[28:29], v[12:13]
	v_mov_b64_e32 v[26:27], v[10:11]
	v_mov_b64_e32 v[24:25], v[8:9]
	v_mov_b64_e32 v[22:23], v[6:7]
	v_mov_b64_e32 v[20:21], v[4:5]
	v_mov_b64_e32 v[18:19], v[2:3]
	v_mov_b64_e32 v[16:17], v[0:1]
	s_mov_b32 s4, 0
	s_waitcnt lgkmcnt(0)
	s_barrier
	s_mov_b32 s98, 0
	s_mov_b32 s99, 0xaa00
	s_cmp_eq_u32 s100, 0
	s_cbranch_scc1 .Latt1_nostag
	s_barrier
.Latt1_nostag:
.LBB0_2127:
	s_add_i32 s2, s4, 1
	s_mov_b32 s5, s99
	v_lshl_add_u32 v32, v163, 1, s5
	s_waitcnt vmcnt(1)
	ds_write_b128 v32, v[124:127]
	v_lshl_add_u32 v32, v167, 1, s5
	ds_write_b128 v32, v[120:123]
	v_lshl_add_u32 v32, v168, 1, s5
	ds_write_b128 v32, v[128:131]
	v_lshl_add_u32 v32, v146, 1, s5
	v_add_u32_e32 v32, 0x6800, v32
	ds_write2_b64 v32, v[132:133], v[134:135] offset1:1
	v_lshl_add_u32 v32, v148, 1, s5
	v_add_u32_e32 v32, 0x6800, v32
	s_cmp_gt_u32 s4, 31
	s_waitcnt vmcnt(0)
	ds_write2_b64 v32, v[136:137], v[138:139] offset1:1
	s_cbranch_scc1 .LBB0_2129
	v_lshl_add_u64 v[32:33], s[6:7], 0, v[154:155]
	v_lshl_add_u64 v[34:35], s[6:7], 0, v[156:157]
	global_load_dwordx4 v[124:127], v[32:33], off
	global_load_dwordx4 v[120:123], v[34:35], off
	v_lshl_add_u64 v[32:33], s[6:7], 0, v[158:159]
	v_lshl_add_u64 v[34:35], s[6:7], 0, v[152:153]
	global_load_dwordx4 v[128:131], v[32:33], off
	global_load_dwordx4 v[132:135], v[34:35], off
	v_lshl_add_u64 v[32:33], s[6:7], 0, v[150:151]
	global_load_dwordx4 v[136:139], v[32:33], off
.LBB0_2129:
	s_mov_b32 s4, s98
	v_add3_u32 v171, s4, v169, v170
	ds_read_b128 v[32:35], v171
	ds_read_b128 v[174:177], v171 offset:32
	s_waitcnt lgkmcnt(1)
	v_mfma_f32_32x32x16_bf16 v[80:95], v[32:35], v[108:111], 0
	ds_read_b128 v[32:35], v171 offset:6656
	ds_read_b128 v[178:181], v171 offset:6688
	s_waitcnt lgkmcnt(1)
	v_mfma_f32_32x32x16_bf16 v[64:79], v[32:35], v[108:111], 0
	ds_read_b128 v[32:35], v171 offset:13312
	ds_read_b128 v[182:185], v171 offset:13344
	s_waitcnt lgkmcnt(1)
	v_mfma_f32_32x32x16_bf16 v[48:63], v[32:35], v[108:111], 0
	ds_read_b128 v[32:35], v171 offset:19968
	ds_read_b128 v[186:189], v171 offset:20000
	v_mfma_f32_32x32x16_bf16 v[80:95], v[174:177], v[104:107], v[80:95]
	s_waitcnt lgkmcnt(1)
	v_mfma_f32_32x32x16_bf16 v[32:47], v[32:35], v[108:111], 0
	v_mfma_f32_32x32x16_bf16 v[64:79], v[178:181], v[104:107], v[64:79]
	ds_read_b128 v[174:177], v171 offset:64
	ds_read_b128 v[178:181], v171 offset:96
	v_mfma_f32_32x32x16_bf16 v[48:63], v[182:185], v[104:107], v[48:63]
	s_waitcnt lgkmcnt(1)
	v_mfma_f32_32x32x16_bf16 v[80:95], v[174:177], v[100:103], v[80:95]
	ds_read_b128 v[174:177], v171 offset:6720
	ds_read_b128 v[182:185], v171 offset:6752
	v_mfma_f32_32x32x16_bf16 v[32:47], v[186:189], v[104:107], v[32:47]
	s_waitcnt lgkmcnt(1)
	v_mfma_f32_32x32x16_bf16 v[64:79], v[174:177], v[100:103], v[64:79]
	ds_read_b128 v[174:177], v171 offset:13376
	ds_read_b128 v[186:189], v171 offset:13408
	s_waitcnt lgkmcnt(1)
	v_mfma_f32_32x32x16_bf16 v[48:63], v[174:177], v[100:103], v[48:63]
	ds_read_b128 v[174:177], v171 offset:20032
	ds_read_b128 v[190:193], v171 offset:20064
	v_mfma_f32_32x32x16_bf16 v[80:95], v[178:181], v[96:99], v[80:95]
	s_waitcnt lgkmcnt(1)
	v_mfma_f32_32x32x16_bf16 v[32:47], v[174:177], v[100:103], v[32:47]
	ds_read_b128 v[174:177], v171 offset:128
	ds_read_b128 v[178:181], v171 offset:160
	s_waitcnt lgkmcnt(1)
	v_mfma_f32_32x32x16_bf16 v[80:95], v[174:177], v[112:115], v[80:95]
	v_mfma_f32_32x32x16_bf16 v[64:79], v[182:185], v[96:99], v[64:79]
	ds_read_b128 v[174:177], v171 offset:6784
	ds_read_b128 v[182:185], v171 offset:6816
	v_mfma_f32_32x32x16_bf16 v[48:63], v[186:189], v[96:99], v[48:63]
	s_waitcnt lgkmcnt(2)
	v_mfma_f32_32x32x16_bf16 v[80:95], v[178:181], v[116:119], v[80:95]
	s_waitcnt lgkmcnt(1)
	v_mfma_f32_32x32x16_bf16 v[64:79], v[174:177], v[112:115], v[64:79]
	ds_read_b128 v[174:177], v171 offset:13440
	ds_read_b128 v[186:189], v171 offset:13472
	s_nop 7
	v_max_f32_e32 v173, v80, v80
	s_waitcnt lgkmcnt(1)
	v_mfma_f32_32x32x16_bf16 v[48:63], v[174:177], v[112:115], v[48:63]
	ds_read_b128 v[174:177], v171 offset:20096
	ds_read_b128 v[178:181], v171 offset:20128
	v_max_f32_e32 v171, v81, v81
	v_max_f32_e32 v171, v173, v171
	v_max3_f32 v171, v171, v82, v83
	v_max3_f32 v171, v171, v84, v85
	v_max3_f32 v171, v171, v86, v87
	v_max3_f32 v171, v171, v88, v89
	v_mfma_f32_32x32x16_bf16 v[32:47], v[190:193], v[96:99], v[32:47]
	v_max3_f32 v171, v171, v90, v91
	v_max3_f32 v171, v171, v92, v93
	v_max3_f32 v171, v171, v94, v95
	v_mfma_f32_32x32x16_bf16 v[64:79], v[182:185], v[116:119], v[64:79]
	s_waitcnt lgkmcnt(2)
	v_mfma_f32_32x32x16_bf16 v[48:63], v[186:189], v[116:119], v[48:63]
	s_nop 9
	v_max3_f32 v171, v171, v64, v65
	v_max3_f32 v171, v171, v66, v67
	v_max3_f32 v171, v171, v68, v69
	v_max3_f32 v171, v171, v70, v71
	v_max3_f32 v171, v171, v72, v73
	v_max3_f32 v171, v171, v74, v75
	v_max3_f32 v171, v171, v76, v77
	s_waitcnt lgkmcnt(1)
	v_mfma_f32_32x32x16_bf16 v[32:47], v[174:177], v[112:115], v[32:47]
	v_max3_f32 v171, v171, v78, v79
	v_max3_f32 v171, v171, v48, v49
	v_max3_f32 v171, v171, v50, v51
	v_max3_f32 v171, v171, v52, v53
	v_max3_f32 v171, v171, v54, v55
	v_max3_f32 v171, v171, v56, v57
	v_max3_f32 v171, v171, v58, v59
	s_waitcnt lgkmcnt(0)
	v_mfma_f32_32x32x16_bf16 v[32:47], v[178:181], v[116:119], v[32:47]
	v_max3_f32 v171, v171, v60, v61
	v_max3_f32 v171, v171, v62, v63
	s_nop 9
	v_max3_f32 v171, v171, v32, v33
	v_max3_f32 v171, v171, v34, v35
	v_max3_f32 v171, v171, v36, v37
	v_max3_f32 v171, v171, v38, v39
	v_max3_f32 v171, v171, v40, v41
	v_max3_f32 v171, v171, v42, v43
	v_max3_f32 v171, v171, v44, v45
	v_max3_f32 v171, v171, v46, v47
	ds_bpermute_b32 v173, v147, v171
	s_waitcnt lgkmcnt(0)
	v_max3_f32 v171, v172, v171, v173
	v_cmp_gt_f32_e32 vcc, v171, v172
	s_cbranch_vccz .LBB0_2131
	v_sub_f32_e32 v172, v172, v171
	v_exp_f32_e32 v172, v172
	s_nop 0
	v_pk_mul_f32 v[30:31], v[30:31], v[172:173] op_sel_hi:[1,0]
	v_pk_mul_f32 v[28:29], v[28:29], v[172:173] op_sel_hi:[1,0]
	v_pk_mul_f32 v[26:27], v[26:27], v[172:173] op_sel_hi:[1,0]
	v_pk_mul_f32 v[24:25], v[24:25], v[172:173] op_sel_hi:[1,0]
	v_pk_mul_f32 v[22:23], v[22:23], v[172:173] op_sel_hi:[1,0]
	v_pk_mul_f32 v[20:21], v[20:21], v[172:173] op_sel_hi:[1,0]
	v_pk_mul_f32 v[18:19], v[18:19], v[172:173] op_sel_hi:[1,0]
	v_pk_mul_f32 v[16:17], v[16:17], v[172:173] op_sel_hi:[1,0]
	v_pk_mul_f32 v[14:15], v[14:15], v[172:173] op_sel_hi:[1,0]
	v_pk_mul_f32 v[12:13], v[12:13], v[172:173] op_sel_hi:[1,0]
	v_pk_mul_f32 v[10:11], v[10:11], v[172:173] op_sel_hi:[1,0]
	v_pk_mul_f32 v[8:9], v[8:9], v[172:173] op_sel_hi:[1,0]
	v_pk_mul_f32 v[6:7], v[6:7], v[172:173] op_sel_hi:[1,0]
	v_pk_mul_f32 v[4:5], v[4:5], v[172:173] op_sel_hi:[1,0]
	v_pk_mul_f32 v[2:3], v[2:3], v[172:173] op_sel_hi:[1,0]
	v_pk_mul_f32 v[0:1], v[0:1], v[172:173] op_sel_hi:[1,0]
	v_mul_f32_e32 v149, v149, v172
	s_branch .LBB0_2132

.LBB0_2132:
	s_waitcnt lgkmcnt(0)
	s_barrier
	v_sub_f32_e32 v80, v80, v171
	v_exp_f32_e32 v80, v80
	v_sub_f32_e32 v81, v81, v171
	v_exp_f32_e32 v81, v81
	v_sub_f32_e32 v82, v82, v171
	v_exp_f32_e32 v82, v82
	v_sub_f32_e32 v83, v83, v171
	v_exp_f32_e32 v83, v83
	v_sub_f32_e32 v84, v84, v171
	v_add_f32_e32 v172, 0, v80
	v_exp_f32_e32 v84, v84
	v_sub_f32_e32 v85, v85, v171
	v_add_f32_e32 v172, v81, v172
	v_exp_f32_e32 v85, v85
	v_sub_f32_e32 v86, v86, v171
	v_add_f32_e32 v172, v82, v172
	v_exp_f32_e32 v86, v86
	v_sub_f32_e32 v87, v87, v171
	v_add_f32_e32 v172, v83, v172
	v_exp_f32_e32 v87, v87
	v_sub_f32_e32 v88, v88, v171
	v_add_f32_e32 v172, v84, v172
	v_exp_f32_e32 v88, v88
	v_sub_f32_e32 v89, v89, v171
	v_add_f32_e32 v172, v85, v172
	v_exp_f32_e32 v89, v89
	v_sub_f32_e32 v90, v90, v171
	v_add_f32_e32 v172, v86, v172
	v_exp_f32_e32 v90, v90
	v_sub_f32_e32 v91, v91, v171
	v_add_f32_e32 v172, v87, v172
	v_exp_f32_e32 v91, v91
	v_sub_f32_e32 v92, v92, v171
	v_add_f32_e32 v172, v88, v172
	v_exp_f32_e32 v92, v92
	v_sub_f32_e32 v93, v93, v171
	v_add_f32_e32 v172, v89, v172
	v_exp_f32_e32 v93, v93
	v_sub_f32_e32 v94, v94, v171
	v_add_f32_e32 v172, v90, v172
	v_exp_f32_e32 v94, v94
	v_sub_f32_e32 v95, v95, v171
	v_add_f32_e32 v172, v91, v172
	v_exp_f32_e32 v95, v95
	v_sub_f32_e32 v64, v64, v171
	v_add_f32_e32 v172, v92, v172
	v_exp_f32_e32 v173, v64
	v_sub_f32_e32 v64, v65, v171
	v_add_f32_e32 v172, v93, v172
	v_exp_f32_e32 v174, v64
	v_sub_f32_e32 v64, v66, v171
	v_add_f32_e32 v172, v94, v172
	v_exp_f32_e32 v175, v64
	v_sub_f32_e32 v65, v67, v171
	v_add_f32_e32 v64, v95, v172
	v_exp_f32_e32 v172, v65
	v_sub_f32_e32 v65, v68, v171
	v_add_f32_e32 v64, v173, v64
	v_exp_f32_e32 v176, v65
	v_sub_f32_e32 v65, v69, v171
	v_add_f32_e32 v64, v174, v64
	v_exp_f32_e32 v177, v65
	v_sub_f32_e32 v65, v70, v171
	v_add_f32_e32 v64, v175, v64
	v_exp_f32_e32 v178, v65
	v_sub_f32_e32 v65, v71, v171
	v_add_f32_e32 v64, v172, v64
	v_exp_f32_e32 v179, v65
	v_sub_f32_e32 v65, v72, v171
	v_add_f32_e32 v64, v176, v64
	v_exp_f32_e32 v72, v65
	v_sub_f32_e32 v65, v73, v171
	v_add_f32_e32 v64, v177, v64
	v_exp_f32_e32 v73, v65
	v_sub_f32_e32 v65, v74, v171
	v_add_f32_e32 v64, v178, v64
	v_exp_f32_e32 v74, v65
	v_sub_f32_e32 v65, v75, v171
	v_add_f32_e32 v64, v179, v64
	v_exp_f32_e32 v75, v65
	v_sub_f32_e32 v65, v76, v171
	v_add_f32_e32 v64, v72, v64
	v_exp_f32_e32 v76, v65
	v_sub_f32_e32 v65, v77, v171
	v_add_f32_e32 v64, v73, v64
	v_exp_f32_e32 v77, v65
	v_sub_f32_e32 v65, v78, v171
	v_add_f32_e32 v64, v74, v64
	v_exp_f32_e32 v78, v65
	v_sub_f32_e32 v65, v79, v171
	v_add_f32_e32 v64, v75, v64
	v_exp_f32_e32 v79, v65
	v_sub_f32_e32 v48, v48, v171
	v_add_f32_e32 v64, v76, v64
	v_exp_f32_e32 v180, v48
	v_sub_f32_e32 v48, v49, v171
	v_add_f32_e32 v64, v77, v64
	v_exp_f32_e32 v181, v48
	v_sub_f32_e32 v48, v50, v171
	v_add_f32_e32 v64, v78, v64
	v_exp_f32_e32 v182, v48
	v_add_f32_e32 v48, v79, v64
	v_add_f32_e32 v48, v180, v48
	v_add_f32_e32 v48, v181, v48
	v_add_f32_e32 v183, v182, v48
	v_sub_f32_e32 v48, v51, v171
	v_exp_f32_e32 v184, v48
	v_sub_f32_e32 v48, v52, v171
	v_add3_u32 v52, s4, v142, v162
	v_exp_f32_e32 v185, v48
	v_sub_f32_e32 v48, v53, v171
	v_add_u32_e32 v187, 0x6800, v52
	v_exp_f32_e32 v186, v48
	ds_read2_b64 v[48:51], v187 offset1:2
	v_sub_f32_e32 v53, v54, v171
	v_exp_f32_e32 v188, v53
	v_cvt_pk_bf16_f32 v64, v80, v81
	v_cvt_pk_bf16_f32 v65, v82, v83
	v_cvt_pk_bf16_f32 v66, v84, v85
	v_cvt_pk_bf16_f32 v67, v86, v87
	v_add_u32_e32 v80, 0x8800, v52
	ds_read2_b64 v[68:71], v80 offset0:32 offset1:34
	s_waitcnt lgkmcnt(1)
	v_mfma_f32_32x32x16_bf16 v[16:31], v[48:51], v[64:67], v[16:31]
	v_add_f32_e32 v48, v184, v183
	v_add_f32_e32 v48, v185, v48
	v_add_f32_e32 v48, v186, v48
	v_add_f32_e32 v81, v188, v48
	v_sub_f32_e32 v48, v55, v171
	v_exp_f32_e32 v82, v48
	ds_read2_b64 v[48:51], v187 offset0:4 offset1:6
	v_sub_f32_e32 v52, v56, v171
	s_waitcnt lgkmcnt(1)
	v_mfma_f32_32x32x16_bf16 v[0:15], v[68:71], v[64:67], v[0:15]
	v_exp_f32_e32 v68, v52
	v_cvt_pk_bf16_f32 v52, v88, v89
	v_cvt_pk_bf16_f32 v53, v90, v91
	v_cvt_pk_bf16_f32 v54, v92, v93
	v_cvt_pk_bf16_f32 v55, v94, v95
	ds_read2_b64 v[64:67], v80 offset0:36 offset1:38
	v_sub_f32_e32 v32, v32, v171
	s_waitcnt lgkmcnt(1)
	v_mfma_f32_32x32x16_bf16 v[16:31], v[48:51], v[52:55], v[16:31]
	v_add_f32_e32 v48, v82, v81
	v_add_f32_e32 v69, v68, v48
	v_sub_f32_e32 v48, v57, v171
	v_exp_f32_e32 v70, v48
	v_sub_f32_e32 v48, v58, v171
	v_exp_f32_e32 v71, v48
	ds_read2_b64 v[48:51], v187 offset0:8 offset1:10
	s_waitcnt lgkmcnt(1)
	v_mfma_f32_32x32x16_bf16 v[0:15], v[64:67], v[52:55], v[0:15]
	v_sub_f32_e32 v52, v59, v171
	ds_read2_b64 v[56:59], v80 offset0:40 offset1:42
	v_exp_f32_e32 v64, v52
	v_cvt_pk_bf16_f32 v52, v173, v174
	v_cvt_pk_bf16_f32 v53, v175, v172
	v_cvt_pk_bf16_f32 v54, v176, v177
	v_cvt_pk_bf16_f32 v55, v178, v179
	v_exp_f32_e32 v65, v32
	v_sub_f32_e32 v32, v33, v171
	s_waitcnt lgkmcnt(1)
	v_mfma_f32_32x32x16_bf16 v[16:31], v[48:51], v[52:55], v[16:31]
	v_sub_f32_e32 v48, v60, v171
	v_exp_f32_e32 v60, v48
	v_sub_f32_e32 v48, v61, v171
	v_exp_f32_e32 v61, v48
	v_sub_f32_e32 v48, v62, v171
	v_exp_f32_e32 v62, v48
	ds_read2_b64 v[48:51], v187 offset0:12 offset1:14
	s_waitcnt lgkmcnt(1)
	v_mfma_f32_32x32x16_bf16 v[0:15], v[56:59], v[52:55], v[0:15]
	ds_read2_b64 v[56:59], v80 offset0:44 offset1:46
	v_sub_f32_e32 v52, v63, v171
	v_exp_f32_e32 v63, v52
	v_cvt_pk_bf16_f32 v52, v72, v73
	v_cvt_pk_bf16_f32 v53, v74, v75
	v_cvt_pk_bf16_f32 v54, v76, v77
	v_cvt_pk_bf16_f32 v55, v78, v79
	v_exp_f32_e32 v66, v32
	v_sub_f32_e32 v32, v34, v171
	s_waitcnt lgkmcnt(1)
	v_mfma_f32_32x32x16_bf16 v[16:31], v[48:51], v[52:55], v[16:31]
	ds_read2_b64 v[48:51], v187 offset0:16 offset1:18
	v_exp_f32_e32 v67, v32
	v_sub_f32_e32 v32, v35, v171
	v_cvt_pk_bf16_f32 v33, v182, v184
	v_cvt_pk_bf16_f32 v34, v185, v186
	v_cvt_pk_bf16_f32 v35, v188, v82
	v_sub_f32_e32 v36, v36, v171
	s_waitcnt lgkmcnt(1)
	v_mfma_f32_32x32x16_bf16 v[0:15], v[56:59], v[52:55], v[0:15]
	ds_read2_b64 v[52:55], v80 offset0:48 offset1:50
	v_exp_f32_e32 v56, v32
	v_cvt_pk_bf16_f32 v32, v180, v181
	v_exp_f32_e32 v57, v36
	v_sub_f32_e32 v36, v37, v171
	v_exp_f32_e32 v58, v36
	v_sub_f32_e32 v36, v38, v171
	s_waitcnt lgkmcnt(1)
	v_mfma_f32_32x32x16_bf16 v[16:31], v[48:51], v[32:35], v[16:31]
	ds_read2_b64 v[48:51], v187 offset0:20 offset1:22
	v_exp_f32_e32 v59, v36
	v_sub_f32_e32 v40, v40, v171
	v_lshl_add_u64 v[150:151], v[150:151], 0, s[16:17]
	v_lshl_add_u64 v[152:153], v[152:153], 0, s[16:17]
	v_lshl_add_u64 v[154:155], v[154:155], 0, s[14:15]
	v_lshl_add_u64 v[156:157], v[156:157], 0, s[14:15]
	s_waitcnt lgkmcnt(1)
	v_mfma_f32_32x32x16_bf16 v[0:15], v[52:55], v[32:35], v[0:15]
	v_sub_f32_e32 v32, v39, v171
	ds_read2_b64 v[36:39], v80 offset0:52 offset1:54
	v_exp_f32_e32 v52, v32
	v_cvt_pk_bf16_f32 v32, v68, v70
	v_cvt_pk_bf16_f32 v33, v71, v64
	v_cvt_pk_bf16_f32 v34, v60, v61
	v_cvt_pk_bf16_f32 v35, v62, v63
	v_exp_f32_e32 v53, v40
	v_sub_f32_e32 v40, v41, v171
	s_waitcnt lgkmcnt(1)
	v_mfma_f32_32x32x16_bf16 v[16:31], v[48:51], v[32:35], v[16:31]
	ds_read2_b64 v[48:51], v187 offset0:24 offset1:26
	v_exp_f32_e32 v54, v40
	v_sub_f32_e32 v40, v42, v171
	v_exp_f32_e32 v55, v40
	v_sub_f32_e32 v40, v44, v171
	v_exp_f32_e32 v44, v40
	v_sub_f32_e32 v40, v45, v171
	s_waitcnt lgkmcnt(1)
	v_mfma_f32_32x32x16_bf16 v[0:15], v[36:39], v[32:35], v[0:15]
	ds_read2_b64 v[36:39], v80 offset0:56 offset1:58
	v_sub_f32_e32 v32, v43, v171
	v_exp_f32_e32 v45, v40
	v_sub_f32_e32 v40, v46, v171
	v_exp_f32_e32 v68, v32
	v_cvt_pk_bf16_f32 v32, v65, v66
	v_cvt_pk_bf16_f32 v33, v67, v56
	v_cvt_pk_bf16_f32 v34, v57, v58
	v_cvt_pk_bf16_f32 v35, v59, v52
	v_exp_f32_e32 v46, v40
	ds_read2_b64 v[40:43], v187 offset0:28 offset1:30
	s_waitcnt lgkmcnt(2)
	v_mfma_f32_32x32x16_bf16 v[16:31], v[48:51], v[32:35], v[16:31]
	s_cmp_lg_u32 s2, 33
	v_lshl_add_u64 v[158:159], v[158:159], 0, s[14:15]
	s_waitcnt lgkmcnt(1)
	v_mfma_f32_32x32x16_bf16 v[0:15], v[36:39], v[32:35], v[0:15]
	v_sub_f32_e32 v32, v47, v171
	v_exp_f32_e32 v47, v32
	ds_read2_b64 v[36:39], v80 offset0:60 offset1:62
	v_cvt_pk_bf16_f32 v32, v53, v54
	v_cvt_pk_bf16_f32 v33, v55, v68
	v_cvt_pk_bf16_f32 v34, v44, v45
	v_cvt_pk_bf16_f32 v35, v46, v47
	s_waitcnt lgkmcnt(0)
	s_barrier
	v_mfma_f32_32x32x16_bf16 v[16:31], v[40:43], v[32:35], v[16:31]
	v_add_f32_e32 v40, v70, v69
	v_add_f32_e32 v40, v71, v40
	v_add_f32_e32 v40, v64, v40
	v_add_f32_e32 v40, v60, v40
	v_add_f32_e32 v40, v61, v40
	v_add_f32_e32 v40, v62, v40
	v_add_f32_e32 v40, v63, v40
	v_mfma_f32_32x32x16_bf16 v[0:15], v[36:39], v[32:35], v[0:15]
	v_add_f32_e32 v32, v65, v40
	v_add_f32_e32 v32, v66, v32
	v_add_f32_e32 v32, v67, v32
	v_add_f32_e32 v32, v56, v32
	v_add_f32_e32 v32, v57, v32
	v_add_f32_e32 v32, v58, v32
	v_add_f32_e32 v32, v59, v32
	v_add_f32_e32 v32, v52, v32
	v_add_f32_e32 v32, v53, v32
	v_add_f32_e32 v32, v54, v32
	v_add_f32_e32 v32, v55, v32
	v_add_f32_e32 v32, v68, v32
	v_add_f32_e32 v32, v44, v32
	v_add_f32_e32 v32, v45, v32
	v_add_f32_e32 v32, v46, v32
	v_add_f32_e32 v32, v47, v32
	v_add_f32_e32 v149, v149, v32
	s_cbranch_scc0 .LBB0_2123
	v_mov_b32_e32 v172, v171
	s_mov_b32 s4, s2
	s_mov_b32 s98, s99
	s_add_i32 s99, s99, 0xaa00
	s_cmp_lt_u32 s99, 0x1fe00
	s_cselect_b32 s99, s99, 0
	s_branch .LBB0_2127

	.amdhsa_kernel _Z11mega_kernel6Params
		.amdhsa_group_segment_fixed_size 0
		.amdhsa_private_segment_fixed_size 0
		.amdhsa_kernarg_size 472
		.amdhsa_user_sgpr_count 2
		.amdhsa_user_sgpr_dispatch_ptr 0
		.amdhsa_user_sgpr_queue_ptr 0
		.amdhsa_user_sgpr_kernarg_segment_ptr 1
		.amdhsa_user_sgpr_dispatch_id 0
		.amdhsa_user_sgpr_kernarg_preload_length 0
		.amdhsa_user_sgpr_kernarg_preload_offset 0
		.amdhsa_user_sgpr_private_segment_size 0
		.amdhsa_uses_dynamic_stack 0
		.amdhsa_enable_private_segment 0
		.amdhsa_system_sgpr_workgroup_id_x 1
		.amdhsa_system_sgpr_workgroup_id_y 0
		.amdhsa_system_sgpr_workgroup_id_z 0
		.amdhsa_system_sgpr_workgroup_info 0
		.amdhsa_system_vgpr_workitem_id 2
		.amdhsa_next_free_vgpr 256
		.amdhsa_next_free_sgpr 102
		.amdhsa_accum_offset 256
		.amdhsa_reserve_vcc 1
		.amdhsa_float_round_mode_32 0
		.amdhsa_float_round_mode_16_64 0
		.amdhsa_float_denorm_mode_32 3
		.amdhsa_float_denorm_mode_16_64 3
		.amdhsa_dx10_clamp 1
		.amdhsa_ieee_mode 1
		.amdhsa_fp16_overflow 0
		.amdhsa_tg_split 0
		.amdhsa_exception_fp_ieee_invalid_op 0
		.amdhsa_exception_fp_denorm_src 0
		.amdhsa_exception_fp_ieee_div_zero 0
		.amdhsa_exception_fp_ieee_overflow 0
		.amdhsa_exception_fp_ieee_underflow 0
		.amdhsa_exception_fp_ieee_inexact 0
		.amdhsa_exception_int_div_zero 0
	.end_amdhsa_kernel

amdhsa.kernels:
  - .agpr_count:     0
    .args:
      - .offset:         0
        .size:           216
        .value_kind:     by_value
      - .offset:         216
        .size:           4
        .value_kind:     hidden_block_count_x
      - .offset:         220
        .size:           4
        .value_kind:     hidden_block_count_y
      - .offset:         224
        .size:           4
        .value_kind:     hidden_block_count_z
      - .offset:         228
        .size:           2
        .value_kind:     hidden_group_size_x
      - .offset:         230
        .size:           2
        .value_kind:     hidden_group_size_y
      - .offset:         232
        .size:           2
        .value_kind:     hidden_group_size_z
      - .offset:         234
        .size:           2
        .value_kind:     hidden_remainder_x
      - .offset:         236
        .size:           2
        .value_kind:     hidden_remainder_y
      - .offset:         238
        .size:           2
        .value_kind:     hidden_remainder_z
      - .offset:         256
        .size:           8
        .value_kind:     hidden_global_offset_x
      - .offset:         264
        .size:           8
        .value_kind:     hidden_global_offset_y
      - .offset:         272
        .size:           8
        .value_kind:     hidden_global_offset_z
      - .offset:         280
        .size:           2
        .value_kind:     hidden_grid_dims
      - .offset:         304
        .size:           8
        .value_kind:     hidden_multigrid_sync_arg
      - .offset:         336
        .size:           4
        .value_kind:     hidden_dynamic_lds_size
    .group_segment_fixed_size: 0
    .kernarg_segment_align: 8
    .kernarg_segment_size: 472
    .language:       OpenCL C
    .language_version:
      - 2
      - 0
    .max_flat_workgroup_size: 512
    .name:           _Z11mega_kernel6Params
    .private_segment_fixed_size: 0
    .sgpr_count:     108
    .sgpr_spill_count: 44
    .symbol:         _Z11mega_kernel6Params.kd
    .uniform_work_group_size: 1
    .uses_dynamic_stack: false
    .vgpr_count:     256
    .vgpr_spill_count: 0
    .wavefront_size: 64
